# scan step loop rewritten: one wave per SIMD, 8 state elements per lane (8-lane DPP reductions, pair-merged y reductions), counted LDS waits
# speedup vs baseline: 1.0107x; 1.0107x over previous
; __device__ __forceinline__ int tidx() { int t = threadIdx.x; asm volatile("" : "+v"(t)); return t; }
; __device__ __forceinline__ const float* kin(int i) { KArgs* k = (KArgs*)__builtin_amdgcn_kernarg_segment_ptr(); return *(const float* const volatile __attribute__((address_space(4)))*)&k->in[i]; }
; __device__ __forceinline__ unsigned char* kws() { KArgs* k = (KArgs*)__builtin_amdgcn_kernarg_segment_ptr(); return *(unsigned char* const volatile __attribute__((address_space(4)))*)&k->ws; }
; __device__ __forceinline__ float* kout() { KArgs* k = (KArgs*)__builtin_amdgcn_kernarg_segment_ptr(); return *(float* const volatile __attribute__((address_space(4)))*)&k->out; }
; __device__ __forceinline__ void scan_block(unsigned char* shm, int sid, int half) {
;     const int tid = tidx(), lane = tid & 63, wid = __builtin_amdgcn_readfirstlane(tid >> 6), nr = lane >> 4, g = lane & 15, rowl = wid * 4 + nr;
;     const int dir = sid >> 6, b = (sid >> 4) & 3, h = sid & 15;
;     const bf16_t* XR = (const bf16_t*)(kws() + WS_XR); const bf16_t* XK = (const bf16_t*)(kws() + WS_XK); const bf16_t* XV = (const bf16_t*)(kws() + WS_XV); const bf16_t* KK = (const bf16_t*)(kws() + WS_KK);
;     const bf16_t* Z = (const bf16_t*)(kws() + WS_P);
;     bf16_t* Y = (bf16_t*)((unsigned char*)kout() + (dir ? DO_YB : DO_YF));
;     constexpr int TS = 32, NCH = (CTX + SEQ) / TS;
;     float* bufs = (float*)shm;
;     float* yst = (float*)(shm + 98304);
;     const int ss = tid >> 4, part = tid & 15;
;     float ka[4];
; #pragma unroll
;     for (int e = 0; e < 4; ++e) ka[e] = kin(20)[h * 64 + 4 * part + e];
;     u32x2 lr, lk, lv, lkk, le, li;
;     ...
;     SCAN_LOAD(0); SCAN_STORE(0);
;     __syncthreads();
.LBB0_782:
	s_lshl_b32 s2, s7, 4
	s_and_b32 s2, s2, 0x70
	s_ashr_i32 s18, s7, 4
	s_add_i32 s2, s2, s18
	v_mov_b32_e32 v4, v219
	s_cmp_lt_u32 s2, 64
	s_load_dwordx2 s[4:5], s[72:73], 0x140
	s_load_dwordx2 s[12:13], s[72:73], 0x140
	s_load_dwordx2 s[14:15], s[72:73], 0x140
	s_load_dwordx2 s[10:11], s[72:73], 0x140
	s_load_dwordx2 s[8:9], s[72:73], 0x140
	s_load_dwordx2 s[16:17], s[72:73], 0x138
	s_cselect_b64 s[38:39], -1, 0
	s_lshl_b32 s20, s18, 6
	s_load_dwordx2 s[18:19], s[72:73], 0xa0
	v_and_b32_e32 v1, 15, v4
	s_and_b32 s20, s20, 0x3c0
	v_lshlrev_b32_e32 v0, 2, v1
	v_or_b32_e32 v66, s20, v0
	v_lshlrev_b32_e32 v2, 2, v66
	s_waitcnt lgkmcnt(0)
	global_load_dword v68, v2, s[18:19]
	s_load_dwordx2 s[18:19], s[72:73], 0xa0
	v_ashrrev_i32_e32 v95, 4, v4
	v_readfirstlane_b32 s21, v4
	s_bfe_u32 s22, s2, 0x20004
	v_cmp_lt_i32_e32 vcc, s0, v95
	s_waitcnt lgkmcnt(0)
	global_load_dword v69, v2, s[18:19] offset:4
	s_load_dwordx2 s[18:19], s[72:73], 0xa0
	s_waitcnt lgkmcnt(0)
	global_load_dword v70, v2, s[18:19] offset:8
	s_load_dwordx2 s[18:19], s[72:73], 0xa0
	s_waitcnt lgkmcnt(0)
	global_load_dword v71, v2, s[18:19] offset:12
	s_and_saveexec_b64 s[18:19], vcc
	s_xor_b64 s[18:19], exec, s[18:19]
	v_sub_u32_e32 v2, 0x10ff, v95
	v_add_u32_e32 v3, 0xffffff00, v95
	s_lshl_b32 s24, s22, 8
	s_lshl_b32 s23, s22, 12
	v_cndmask_b32_e64 v2, v2, v3, s[38:39]
	s_bitset1_b32 s24, 14
	v_add_u32_e32 v2, s23, v2
	v_mov_b32_e32 v67, s24
	v_mov_b32_e32 v94, s23
	s_andn2_saveexec_b64 s[18:19], s[18:19]
	s_lshl_b32 s23, s22, 8
	v_sub_u32_e32 v2, 0xff, v95
	s_bitset1_b32 s23, 14
	v_cndmask_b32_e64 v2, v2, v95, s[38:39]
	s_lshl_b32 s22, s22, 12
	v_add_u32_e32 v2, s23, v2
	v_mov_b32_e32 v67, s23
	v_mov_b32_e32 v94, s22
	s_or_b64 exec, exec, s[18:19]
	s_ashr_i32 s21, s21, 4
	s_and_b64 s[18:19], s[38:39], exec
	s_cselect_b32 s18, 0, 0x2200000
	s_add_u32 s18, s16, s18
	s_addc_u32 s17, s17, 0
	s_add_u32 s4, s4, 0x1ba00000
	s_addc_u32 s5, s5, 0
	s_add_u32 s12, s12, 0x1dc00000
	s_addc_u32 s13, s13, 0
	s_add_u32 s40, s14, 0x1fe00000
	s_addc_u32 s41, s15, 0
	v_ashrrev_i32_e32 v3, 31, v2
	s_add_u32 s42, s10, 0x22000000
	v_lshlrev_b64 v[6:7], 11, v[2:3]
	v_lshl_or_b32 v6, v66, 1, v6
	s_addc_u32 s43, s11, 0
	v_lshl_add_u64 v[8:9], s[4:5], 0, v[6:7]
	s_add_u32 s8, s8, 0x11000000
	global_load_dwordx2 v[72:73], v[8:9], off
	s_addc_u32 s9, s9, 0
	v_lshl_add_u64 v[8:9], s[12:13], 0, v[6:7]
	s_lshl_b32 s2, s2, 4
	global_load_dwordx2 v[74:75], v[8:9], off
	s_and_b32 s10, s2, 0xfffffc00
	v_lshl_add_u64 v[8:9], s[40:41], 0, v[6:7]
	v_lshl_add_u64 v[6:7], s[42:43], 0, v[6:7]
	s_ashr_i32 s11, s10, 31
	global_load_dwordx2 v[78:79], v[6:7], off
	v_mov_b64_e32 v[6:7], s[8:9]
	v_mad_i64_i32 v[2:3], s[14:15], v2, s1, v[6:7]
	s_lshl_b64 s[10:11], s[10:11], 1
	v_lshl_add_u64 v[2:3], v[2:3], 0, s[10:11]
	s_lshl_b32 s2, s20, 1
	v_lshl_add_u64 v[2:3], v[2:3], 0, s[2:3]
	v_lshlrev_b32_e32 v64, 1, v0
	global_load_dwordx2 v[76:77], v[8:9], off
	v_lshl_add_u64 v[2:3], v[2:3], 0, v[64:65]
	s_movk_i32 s14, 0x1000
	global_load_dwordx2 v[80:81], v[2:3], off
	v_add_co_u32_e32 v2, vcc, s14, v2
	v_lshlrev_b32_e32 v5, 2, v0
	s_nop 0
	v_addc_co_u32_e32 v3, vcc, 0, v3, vcc
	global_load_dwordx2 v[82:83], v[2:3], off
	v_lshrrev_b32_e32 v2, 4, v4
	v_lshlrev_b32_e32 v3, 8, v95
	v_lshlrev_b32_e32 v4, 2, v4
	s_waitcnt vmcnt(17)
	v_bfi_b32 v18, -4, s21, v2
	v_add3_u32 v96, 0, v3, v5
	v_and_b32_e32 v97, 60, v4
	s_add_u32 s8, s8, s10
	s_addc_u32 s9, s9, s11
	s_add_u32 s8, s8, s2
	s_addc_u32 s9, s9, 0
	s_lshl_b32 s10, s7, 2
	s_and_b32 s10, s10, 32
	s_add_u32 s2, s18, s2
	v_lshl_add_u64 v[84:85], s[8:9], 0, v[64:65]
	s_addc_u32 s9, s17, 0
	s_lshl_b32 s8, s10, 1
	s_add_u32 s8, s2, s8
	s_addc_u32 s9, s9, 0
	s_mov_b32 s16, 0
	v_lshlrev_b32_e32 v98, 7, v95
	v_sub_u32_e32 v99, 0, v95
	v_lshlrev_b32_e32 v100, 2, v18
	s_lshl_b32 s2, s10, 2
	s_mov_b32 s11, 0
	s_waitcnt vmcnt(5)
	v_lshlrev_b32_e32 v2, 16, v72
	v_and_b32_e32 v3, 0xffff0000, v72
	v_lshlrev_b32_e32 v4, 16, v73
	v_and_b32_e32 v5, 0xffff0000, v73
	ds_write_b128 v96, v[2:5] offset:32768
	s_waitcnt vmcnt(4)
	v_lshlrev_b32_e32 v6, 16, v74
	v_and_b32_e32 v7, 0xffff0000, v74
	v_lshlrev_b32_e32 v8, 16, v75
	v_and_b32_e32 v9, 0xffff0000, v75
	s_waitcnt vmcnt(3)
	v_lshlrev_b32_e32 v10, 16, v78
	v_and_b32_e32 v11, 0xffff0000, v78
	v_lshlrev_b32_e32 v12, 16, v79
	v_and_b32_e32 v13, 0xffff0000, v79
	s_waitcnt vmcnt(2)
	v_lshlrev_b32_e32 v2, 16, v76
	v_and_b32_e32 v3, 0xffff0000, v76
	v_lshlrev_b32_e32 v4, 16, v77
	v_and_b32_e32 v5, 0xffff0000, v77
	ds_write_b128 v96, v[2:5] offset:40960
	v_xor_b32_e32 v5, 0x80000000, v13
	v_xor_b32_e32 v4, 0x80000000, v12
	v_xor_b32_e32 v3, 0x80000000, v11
	v_xor_b32_e32 v2, 0x80000000, v10
	ds_write_b128 v96, v[2:5] offset:8192
	s_waitcnt vmcnt(1)
	v_lshlrev_b32_e32 v2, 16, v80
	v_and_b32_e32 v3, 0xffff0000, v80
	v_lshlrev_b32_e32 v4, 16, v81
	v_and_b32_e32 v5, 0xffff0000, v81
	s_waitcnt vmcnt(0)
	v_lshlrev_b32_e32 v14, 16, v82
	v_and_b32_e32 v15, 0xffff0000, v82
	v_lshlrev_b32_e32 v16, 16, v83
	v_and_b32_e32 v17, 0xffff0000, v83
	v_sub_f32_e32 v5, 1.0, v5
	v_sub_f32_e32 v4, 1.0, v4
	v_sub_f32_e32 v3, 1.0, v3
	v_sub_f32_e32 v2, 1.0, v2
	ds_write_b128 v96, v[2:5]
	v_pk_mul_f32 v[4:5], v[12:13], v[16:17]
	v_pk_mul_f32 v[2:3], v[10:11], v[14:15]
	v_pk_add_f32 v[10:11], v[16:17], -1.0 op_sel_hi:[1,0]
	v_pk_add_f32 v[12:13], v[14:15], -1.0 op_sel_hi:[1,0]
	ds_write_b128 v96, v[2:5] offset:16384
	v_pk_fma_f32 v[2:3], v[68:69], v[12:13], 1.0 op_sel_hi:[1,1,0]
	v_pk_fma_f32 v[4:5], v[70:71], v[10:11], 1.0 op_sel_hi:[1,1,0]
	v_pk_mul_f32 v[2:3], v[2:3], v[6:7]
	v_pk_mul_f32 v[4:5], v[4:5], v[8:9]
	ds_write_b128 v96, v[2:5] offset:24576
	v_lshlrev_b32_e32 v2, 1, v1
	v_mov_b32_e32 v1, v65
	v_lshl_add_u64 v[86:87], s[8:9], 0, v[0:1]
	v_mov_b32_e32 v0, 0
	v_lshlrev_b32_e32 v101, 2, v2
	v_mov_b32_e32 v1, v0
	v_mov_b32_e32 v2, v0
	v_mov_b32_e32 v3, v0
	v_mov_b32_e32 v6, v0
	v_mov_b32_e32 v7, v0
	v_mov_b32_e32 v8, v0
	v_readfirstlane_b32 s44, v219
	s_lshr_b32 s44, s44, 6
	v_and_b32_e32 v136, 63, v219
	v_and_b32_e32 v130, 7, v136
	v_lshlrev_b32_e32 v130, 5, v130
	v_lshrrev_b32_e32 v131, 3, v136
	v_lshl_add_u32 v131, s44, 3, v131
	v_lshlrev_b32_e32 v131, 2, v131
	v_bfe_u32 v132, v136, 2, 1
	v_lshlrev_b32_e32 v132, 7, v132
	v_mov_b32_e32 v122, 0
	v_mov_b32_e32 v123, 0
	v_mov_b32_e32 v124, 0
	v_mov_b32_e32 v125, 0
	v_mov_b32_e32 v126, 0
	v_mov_b32_e32 v127, 0
	v_mov_b32_e32 v128, 0
	v_mov_b32_e32 v129, 0
	s_waitcnt lgkmcnt(0)
	s_barrier
	s_branch .LBB0_788

; template <int CTRL> __device__ __forceinline__ float dppf(float x) { return __builtin_bit_cast(float, __builtin_amdgcn_mov_dpp(__builtin_bit_cast(int, x), CTRL, 0xf, 0xf, true)); }
; #define LDOPS(s_) do { const float* p_ = bb + (s_) * 64; w4[(s_) % 3] = *(const f32x4*)(p_); a4[(s_) % 3] = *(const f32x4*)(p_ + 2048); b4[(s_) % 3] = *(const f32x4*)(p_ + 4096); k4[(s_) % 3] = *(const f32x4*)(p_ + 6144); \
;               r4[(s_) % 3] = *(const f32x4*)(p_ + 8192); vv[(s_) % 3] = vb[(s_) * 64]; } while (0)
; #define c opq(blockIdx.x)
; __device__ __forceinline__ void scan_block(unsigned char* shm, int sid, int half) {
;     ...
;         { const float* bb = bufs + (c & 1) * 12288 + 4 * g; float* ys = yst + (c & 1) * 1024 + rowl; const float* vb = bufs + (c & 1) * 12288 + 5 * 2048 + half * 32 + rowl;
;           f32x4 w4[3], a4[3], b4[3], k4[3], r4[3]; float vv[3];
;     ...
;           LDOPS(0); LDOPS(1);
; #pragma unroll
;           for (int s = 0; s < TS; ++s) {
;               const f32x4 a_ = a4[s % 3], w_ = w4[s % 3], b_ = b4[s % 3], k_ = k4[s % 3], r_ = r4[s % 3];
;               const float av[4] = {a_.x, a_.y, a_.z, a_.w}, wv[4] = {w_.x, w_.y, w_.z, w_.w}, bv[4] = {b_.x, b_.y, b_.z, b_.w}, kv[4] = {k_.x, k_.y, k_.z, k_.w}, rv[4] = {r_.x, r_.y, r_.z, r_.w};
;               const float v1 = vv[s % 3];
;               if (s + 2 < TS) LDOPS(s + 2);
;               float t = S[0] * av[0]; t = fmaf(S[1], av[1], t); t = fmaf(S[2], av[2], t); t = fmaf(S[3], av[3], t);
;               t += dppf<0xB1>(t); t += dppf<0x4E>(t); t += dppf<0x141>(t); t += dppf<0x140>(t);
; #pragma unroll
;               for (int q = 0; q < 4; ++q) S[q] = fmaf(S[q], wv[q], fmaf(bv[q], t, kv[q] * v1));
;               float u = S[0] * rv[0]; u = fmaf(S[1], rv[1], u); u = fmaf(S[2], rv[2], u); u = fmaf(S[3], rv[3], u);
;               u += dppf<0xB1>(u); u += dppf<0x4E>(u); u += dppf<0x141>(u); u += dppf<0x140>(u);
;               ys[s * 32] = u;
;           }
.LBB0_794:
	s_and_b32 s8, s11, 1
	s_mul_i32 s9, s8, 0xc000
	s_add_i32 s9, s9, 0
	v_add_u32_e32 v133, s9, v130
	s_add_i32 s9, s9, s2
	v_add_u32_e32 v134, s9, v131
	s_lshl_b32 s8, s8, 12
	s_add_i32 s8, s8, 0
	s_add_i32 s8, s8, 0x18000
	v_add3_u32 v135, s8, v131, v132
	s_add_i32 s10, s11, 1
	s_andn2_b64 vcc, exec, s[14:15]
	s_cmp_ge_u32 s44, 4
	s_cbranch_scc1 .Lscan_idle
	ds_read_b128 v[140:143], v133 offset:8192
	ds_read_b128 v[144:147], v133 offset:8208
	ds_read_b128 v[148:151], v133 offset:24576
	ds_read_b128 v[152:155], v133 offset:24592
	ds_read2st64_b32 v[106:107], v134 offset0:160 offset1:161
	ds_read_b128 v[176:179], v133 offset:0
	ds_read_b128 v[180:183], v133 offset:16
	ds_read_b128 v[184:187], v133 offset:16384
	ds_read_b128 v[188:191], v133 offset:16400
	ds_read_b128 v[192:195], v133 offset:32768
	ds_read_b128 v[196:199], v133 offset:32784
	ds_read_b128 v[158:161], v133 offset:8448
	ds_read_b128 v[162:165], v133 offset:8464
	ds_read_b128 v[166:169], v133 offset:24832
	ds_read_b128 v[170:173], v133 offset:24848
	s_waitcnt lgkmcnt(10)
	v_mul_f32_e32 v136, v122, v140
	v_mul_f32_e32 v112, v148, v106
	v_fmac_f32_e32 v136, v123, v141
	v_mul_f32_e32 v113, v149, v106
	v_fmac_f32_e32 v136, v124, v142
	v_mul_f32_e32 v114, v150, v106
	v_fmac_f32_e32 v136, v125, v143
	v_mul_f32_e32 v115, v151, v106
	v_fmac_f32_e32 v136, v126, v144
	v_mul_f32_e32 v116, v152, v106
	v_fmac_f32_e32 v136, v127, v145
	v_mul_f32_e32 v117, v153, v106
	v_fmac_f32_e32 v136, v128, v146
	v_mul_f32_e32 v118, v154, v106
	v_fmac_f32_e32 v136, v129, v147
	v_mul_f32_e32 v119, v155, v106
	s_nop 0
	v_add_f32_dpp v136, v136, v136 quad_perm:[1,0,3,2] row_mask:0xf bank_mask:0xf bound_ctrl:1
	s_nop 1
	v_add_f32_dpp v136, v136, v136 quad_perm:[2,3,0,1] row_mask:0xf bank_mask:0xf bound_ctrl:1
	s_nop 1
	v_add_f32_dpp v136, v136, v136 row_half_mirror row_mask:0xf bank_mask:0xf bound_ctrl:1
	ds_read_b128 v[140:143], v133 offset:8704
	ds_read_b128 v[144:147], v133 offset:8720
	ds_read_b128 v[148:151], v133 offset:25088
	ds_read_b128 v[152:155], v133 offset:25104
	ds_read2st64_b32 v[108:109], v134 offset0:162 offset1:163
	ds_read_b128 v[32:35], v133 offset:256
	ds_read_b128 v[36:39], v133 offset:272
	ds_read_b128 v[40:43], v133 offset:16640
	ds_read_b128 v[44:47], v133 offset:16656
	ds_read_b128 v[48:51], v133 offset:33024
	ds_read_b128 v[52:55], v133 offset:33040
	s_waitcnt lgkmcnt(11)
	v_fmac_f32_e32 v112, v184, v136
	v_fmac_f32_e32 v113, v185, v136
	v_fmac_f32_e32 v114, v186, v136
	v_fmac_f32_e32 v115, v187, v136
	v_fmac_f32_e32 v116, v188, v136
	v_fmac_f32_e32 v117, v189, v136
	v_fmac_f32_e32 v118, v190, v136
	v_fmac_f32_e32 v119, v191, v136
	v_fma_f32 v122, v122, v176, v112
	v_fma_f32 v123, v123, v177, v113
	v_fma_f32 v124, v124, v178, v114
	v_fma_f32 v125, v125, v179, v115
	v_fma_f32 v126, v126, v180, v116
	v_fma_f32 v127, v127, v181, v117
	v_fma_f32 v128, v128, v182, v118
	v_fma_f32 v129, v129, v183, v119
	v_mul_f32_e32 v136, v122, v158
	v_mul_f32_e32 v137, v192, v122
	v_fmac_f32_e32 v136, v123, v159
	v_fmac_f32_e32 v137, v123, v193
	v_fmac_f32_e32 v136, v124, v160
	v_fmac_f32_e32 v137, v124, v194
	v_fmac_f32_e32 v136, v125, v161
	v_fmac_f32_e32 v137, v125, v195
	v_fmac_f32_e32 v136, v126, v162
	v_fmac_f32_e32 v137, v126, v196
	v_fmac_f32_e32 v136, v127, v163
	v_fmac_f32_e32 v137, v127, v197
	v_fmac_f32_e32 v136, v128, v164
	v_fmac_f32_e32 v137, v128, v198
	v_fmac_f32_e32 v136, v129, v165
	v_fmac_f32_e32 v137, v129, v199
	v_mul_f32_e32 v112, v166, v107
	v_mul_f32_e32 v113, v167, v107
	v_add_f32_dpp v136, v136, v136 quad_perm:[1,0,3,2] row_mask:0xf bank_mask:0xf bound_ctrl:1
	v_mul_f32_e32 v114, v168, v107
	v_mul_f32_e32 v115, v169, v107
	v_add_f32_dpp v136, v136, v136 quad_perm:[2,3,0,1] row_mask:0xf bank_mask:0xf bound_ctrl:1
	v_mul_f32_e32 v116, v170, v107
	v_mul_f32_e32 v117, v171, v107
	v_add_f32_dpp v136, v136, v136 row_half_mirror row_mask:0xf bank_mask:0xf bound_ctrl:1
	v_mul_f32_e32 v118, v172, v107
	v_mul_f32_e32 v119, v173, v107
	ds_read_b128 v[158:161], v133 offset:8960
	ds_read_b128 v[162:165], v133 offset:8976
	ds_read_b128 v[166:169], v133 offset:25344
	ds_read_b128 v[170:173], v133 offset:25360
	ds_read_b128 v[176:179], v133 offset:512
	ds_read_b128 v[180:183], v133 offset:528
	ds_read_b128 v[184:187], v133 offset:16896
	ds_read_b128 v[188:191], v133 offset:16912
	ds_read_b128 v[192:195], v133 offset:33280
	ds_read_b128 v[196:199], v133 offset:33296
	s_waitcnt lgkmcnt(10)
; template <int CTRL> __device__ __forceinline__ float dppf(float x) { return __builtin_bit_cast(float, __builtin_amdgcn_mov_dpp(__builtin_bit_cast(int, x), CTRL, 0xf, 0xf, true)); }
; #define LDOPS(s_) do { const float* p_ = bb + (s_) * 64; w4[(s_) % 3] = *(const f32x4*)(p_); a4[(s_) % 3] = *(const f32x4*)(p_ + 2048); b4[(s_) % 3] = *(const f32x4*)(p_ + 4096); k4[(s_) % 3] = *(const f32x4*)(p_ + 6144); \
;               r4[(s_) % 3] = *(const f32x4*)(p_ + 8192); vv[(s_) % 3] = vb[(s_) * 64]; } while (0)
; __device__ __forceinline__ void scan_block(unsigned char* shm, int sid, int half) {
;     ...
;           for (int s = 0; s < TS; ++s) {
;               const f32x4 a_ = a4[s % 3], w_ = w4[s % 3], b_ = b4[s % 3], k_ = k4[s % 3], r_ = r4[s % 3];
;               const float av[4] = {a_.x, a_.y, a_.z, a_.w}, wv[4] = {w_.x, w_.y, w_.z, w_.w}, bv[4] = {b_.x, b_.y, b_.z, b_.w}, kv[4] = {k_.x, k_.y, k_.z, k_.w}, rv[4] = {r_.x, r_.y, r_.z, r_.w};
;               const float v1 = vv[s % 3];
;               if (s + 2 < TS) LDOPS(s + 2);
;               float t = S[0] * av[0]; t = fmaf(S[1], av[1], t); t = fmaf(S[2], av[2], t); t = fmaf(S[3], av[3], t);
;               t += dppf<0xB1>(t); t += dppf<0x4E>(t); t += dppf<0x141>(t); t += dppf<0x140>(t);
; #pragma unroll
;               for (int q = 0; q < 4; ++q) S[q] = fmaf(S[q], wv[q], fmaf(bv[q], t, kv[q] * v1));
;               float u = S[0] * rv[0]; u = fmaf(S[1], rv[1], u); u = fmaf(S[2], rv[2], u); u = fmaf(S[3], rv[3], u);
;               u += dppf<0xB1>(u); u += dppf<0x4E>(u); u += dppf<0x141>(u); u += dppf<0x140>(u);
;               ys[s * 32] = u;
;           }
	v_fmac_f32_e32 v112, v40, v136
	v_fmac_f32_e32 v113, v41, v136
	v_fmac_f32_e32 v114, v42, v136
	v_fmac_f32_e32 v115, v43, v136
	v_fmac_f32_e32 v116, v44, v136
	v_fmac_f32_e32 v117, v45, v136
	v_fmac_f32_e32 v118, v46, v136
	v_fmac_f32_e32 v119, v47, v136
	v_fma_f32 v122, v122, v32, v112
	v_fma_f32 v123, v123, v33, v113
	v_fma_f32 v124, v124, v34, v114
	v_fma_f32 v125, v125, v35, v115
	v_fma_f32 v126, v126, v36, v116
	v_fma_f32 v127, v127, v37, v117
	v_fma_f32 v128, v128, v38, v118
	v_fma_f32 v129, v129, v39, v119
	v_mul_f32_e32 v136, v122, v140
	v_mul_f32_e32 v138, v48, v122
	v_fmac_f32_e32 v136, v123, v141
	v_fmac_f32_e32 v138, v123, v49
	v_fmac_f32_e32 v136, v124, v142
	v_fmac_f32_e32 v138, v124, v50
	v_fmac_f32_e32 v136, v125, v143
	v_fmac_f32_e32 v138, v125, v51
	v_fmac_f32_e32 v136, v126, v144
	v_fmac_f32_e32 v138, v126, v52
	v_fmac_f32_e32 v136, v127, v145
	v_fmac_f32_e32 v138, v127, v53
	v_fmac_f32_e32 v136, v128, v146
	v_fmac_f32_e32 v138, v128, v54
	v_fmac_f32_e32 v136, v129, v147
	v_fmac_f32_e32 v138, v129, v55
	v_mul_f32_e32 v112, v148, v108
	v_mul_f32_e32 v113, v149, v108
	v_add_f32_dpp v136, v136, v136 quad_perm:[1,0,3,2] row_mask:0xf bank_mask:0xf bound_ctrl:1
	v_add_f32_dpp v139, v137, v137 row_half_mirror row_mask:0xf bank_mask:0xf bound_ctrl:1
	v_add_f32_dpp v139, v138, v138 row_half_mirror row_mask:0xf bank_mask:0xa
	v_add_f32_dpp v136, v136, v136 quad_perm:[2,3,0,1] row_mask:0xf bank_mask:0xf bound_ctrl:1
	v_mul_f32_e32 v114, v150, v108
	v_mul_f32_e32 v115, v151, v108
	v_add_f32_dpp v139, v139, v139 quad_perm:[2,3,0,1] row_mask:0xf bank_mask:0xf bound_ctrl:1
	v_add_f32_dpp v136, v136, v136 row_half_mirror row_mask:0xf bank_mask:0xf bound_ctrl:1
	v_mul_f32_e32 v116, v152, v108
	v_mul_f32_e32 v117, v153, v108
	v_add_f32_dpp v139, v139, v139 quad_perm:[1,0,3,2] row_mask:0xf bank_mask:0xf bound_ctrl:1
	v_mul_f32_e32 v118, v154, v108
	v_mul_f32_e32 v119, v155, v108
	ds_write_b32 v135, v139 offset:0
	ds_read_b128 v[140:143], v133 offset:9216
	ds_read_b128 v[144:147], v133 offset:9232
	ds_read_b128 v[148:151], v133 offset:25600
	ds_read_b128 v[152:155], v133 offset:25616
	ds_read2st64_b32 v[106:107], v134 offset0:164 offset1:165
	ds_read_b128 v[32:35], v133 offset:768
	ds_read_b128 v[36:39], v133 offset:784
	ds_read_b128 v[40:43], v133 offset:17152
	ds_read_b128 v[44:47], v133 offset:17168
	ds_read_b128 v[48:51], v133 offset:33536
	ds_read_b128 v[52:55], v133 offset:33552
	s_waitcnt lgkmcnt(11)
	v_fmac_f32_e32 v112, v184, v136
	v_fmac_f32_e32 v113, v185, v136
	v_fmac_f32_e32 v114, v186, v136
	v_fmac_f32_e32 v115, v187, v136
	v_fmac_f32_e32 v116, v188, v136
	v_fmac_f32_e32 v117, v189, v136
	v_fmac_f32_e32 v118, v190, v136
	v_fmac_f32_e32 v119, v191, v136
	v_fma_f32 v122, v122, v176, v112
	v_fma_f32 v123, v123, v177, v113
	v_fma_f32 v124, v124, v178, v114
	v_fma_f32 v125, v125, v179, v115
	v_fma_f32 v126, v126, v180, v116
	v_fma_f32 v127, v127, v181, v117
	v_fma_f32 v128, v128, v182, v118
	v_fma_f32 v129, v129, v183, v119
	v_mul_f32_e32 v136, v122, v158
	v_mul_f32_e32 v137, v192, v122
	v_fmac_f32_e32 v136, v123, v159
	v_fmac_f32_e32 v137, v123, v193
	v_fmac_f32_e32 v136, v124, v160
	v_fmac_f32_e32 v137, v124, v194
	v_fmac_f32_e32 v136, v125, v161
	v_fmac_f32_e32 v137, v125, v195
	v_fmac_f32_e32 v136, v126, v162
	v_fmac_f32_e32 v137, v126, v196
	v_fmac_f32_e32 v136, v127, v163
	v_fmac_f32_e32 v137, v127, v197
	v_fmac_f32_e32 v136, v128, v164
	v_fmac_f32_e32 v137, v128, v198
	v_fmac_f32_e32 v136, v129, v165
	v_fmac_f32_e32 v137, v129, v199
	v_mul_f32_e32 v112, v166, v109
	v_mul_f32_e32 v113, v167, v109
	v_add_f32_dpp v136, v136, v136 quad_perm:[1,0,3,2] row_mask:0xf bank_mask:0xf bound_ctrl:1
	v_mul_f32_e32 v114, v168, v109
	v_mul_f32_e32 v115, v169, v109
	v_add_f32_dpp v136, v136, v136 quad_perm:[2,3,0,1] row_mask:0xf bank_mask:0xf bound_ctrl:1
	v_mul_f32_e32 v116, v170, v109
	v_mul_f32_e32 v117, v171, v109
	v_add_f32_dpp v136, v136, v136 row_half_mirror row_mask:0xf bank_mask:0xf bound_ctrl:1
	v_mul_f32_e32 v118, v172, v109
	v_mul_f32_e32 v119, v173, v109
	ds_read_b128 v[158:161], v133 offset:9472
	ds_read_b128 v[162:165], v133 offset:9488
	ds_read_b128 v[166:169], v133 offset:25856
	ds_read_b128 v[170:173], v133 offset:25872
	ds_read_b128 v[176:179], v133 offset:1024
	ds_read_b128 v[180:183], v133 offset:1040
	ds_read_b128 v[184:187], v133 offset:17408
	ds_read_b128 v[188:191], v133 offset:17424
	ds_read_b128 v[192:195], v133 offset:33792
	ds_read_b128 v[196:199], v133 offset:33808
	s_waitcnt lgkmcnt(10)
; template <int CTRL> __device__ __forceinline__ float dppf(float x) { return __builtin_bit_cast(float, __builtin_amdgcn_mov_dpp(__builtin_bit_cast(int, x), CTRL, 0xf, 0xf, true)); }
; #define LDOPS(s_) do { const float* p_ = bb + (s_) * 64; w4[(s_) % 3] = *(const f32x4*)(p_); a4[(s_) % 3] = *(const f32x4*)(p_ + 2048); b4[(s_) % 3] = *(const f32x4*)(p_ + 4096); k4[(s_) % 3] = *(const f32x4*)(p_ + 6144); \
;               r4[(s_) % 3] = *(const f32x4*)(p_ + 8192); vv[(s_) % 3] = vb[(s_) * 64]; } while (0)
; __device__ __forceinline__ void scan_block(unsigned char* shm, int sid, int half) {
;     ...
;           for (int s = 0; s < TS; ++s) {
;               const f32x4 a_ = a4[s % 3], w_ = w4[s % 3], b_ = b4[s % 3], k_ = k4[s % 3], r_ = r4[s % 3];
;               const float av[4] = {a_.x, a_.y, a_.z, a_.w}, wv[4] = {w_.x, w_.y, w_.z, w_.w}, bv[4] = {b_.x, b_.y, b_.z, b_.w}, kv[4] = {k_.x, k_.y, k_.z, k_.w}, rv[4] = {r_.x, r_.y, r_.z, r_.w};
;               const float v1 = vv[s % 3];
;               if (s + 2 < TS) LDOPS(s + 2);
;               float t = S[0] * av[0]; t = fmaf(S[1], av[1], t); t = fmaf(S[2], av[2], t); t = fmaf(S[3], av[3], t);
;               t += dppf<0xB1>(t); t += dppf<0x4E>(t); t += dppf<0x141>(t); t += dppf<0x140>(t);
; #pragma unroll
;               for (int q = 0; q < 4; ++q) S[q] = fmaf(S[q], wv[q], fmaf(bv[q], t, kv[q] * v1));
;               float u = S[0] * rv[0]; u = fmaf(S[1], rv[1], u); u = fmaf(S[2], rv[2], u); u = fmaf(S[3], rv[3], u);
;               u += dppf<0xB1>(u); u += dppf<0x4E>(u); u += dppf<0x141>(u); u += dppf<0x140>(u);
;               ys[s * 32] = u;
;           }
	v_fmac_f32_e32 v112, v40, v136
	v_fmac_f32_e32 v113, v41, v136
	v_fmac_f32_e32 v114, v42, v136
	v_fmac_f32_e32 v115, v43, v136
	v_fmac_f32_e32 v116, v44, v136
	v_fmac_f32_e32 v117, v45, v136
	v_fmac_f32_e32 v118, v46, v136
	v_fmac_f32_e32 v119, v47, v136
	v_fma_f32 v122, v122, v32, v112
	v_fma_f32 v123, v123, v33, v113
	v_fma_f32 v124, v124, v34, v114
	v_fma_f32 v125, v125, v35, v115
	v_fma_f32 v126, v126, v36, v116
	v_fma_f32 v127, v127, v37, v117
	v_fma_f32 v128, v128, v38, v118
	v_fma_f32 v129, v129, v39, v119
	v_mul_f32_e32 v136, v122, v140
	v_mul_f32_e32 v138, v48, v122
	v_fmac_f32_e32 v136, v123, v141
	v_fmac_f32_e32 v138, v123, v49
	v_fmac_f32_e32 v136, v124, v142
	v_fmac_f32_e32 v138, v124, v50
	v_fmac_f32_e32 v136, v125, v143
	v_fmac_f32_e32 v138, v125, v51
	v_fmac_f32_e32 v136, v126, v144
	v_fmac_f32_e32 v138, v126, v52
	v_fmac_f32_e32 v136, v127, v145
	v_fmac_f32_e32 v138, v127, v53
	v_fmac_f32_e32 v136, v128, v146
	v_fmac_f32_e32 v138, v128, v54
	v_fmac_f32_e32 v136, v129, v147
	v_fmac_f32_e32 v138, v129, v55
	v_mul_f32_e32 v112, v148, v106
	v_mul_f32_e32 v113, v149, v106
	v_add_f32_dpp v136, v136, v136 quad_perm:[1,0,3,2] row_mask:0xf bank_mask:0xf bound_ctrl:1
	v_add_f32_dpp v139, v137, v137 row_half_mirror row_mask:0xf bank_mask:0xf bound_ctrl:1
	v_add_f32_dpp v139, v138, v138 row_half_mirror row_mask:0xf bank_mask:0xa
	v_add_f32_dpp v136, v136, v136 quad_perm:[2,3,0,1] row_mask:0xf bank_mask:0xf bound_ctrl:1
	v_mul_f32_e32 v114, v150, v106
	v_mul_f32_e32 v115, v151, v106
	v_add_f32_dpp v139, v139, v139 quad_perm:[2,3,0,1] row_mask:0xf bank_mask:0xf bound_ctrl:1
	v_add_f32_dpp v136, v136, v136 row_half_mirror row_mask:0xf bank_mask:0xf bound_ctrl:1
	v_mul_f32_e32 v116, v152, v106
	v_mul_f32_e32 v117, v153, v106
	v_add_f32_dpp v139, v139, v139 quad_perm:[1,0,3,2] row_mask:0xf bank_mask:0xf bound_ctrl:1
	v_mul_f32_e32 v118, v154, v106
	v_mul_f32_e32 v119, v155, v106
	ds_write_b32 v135, v139 offset:256
	ds_read_b128 v[140:143], v133 offset:9728
	ds_read_b128 v[144:147], v133 offset:9744
	ds_read_b128 v[148:151], v133 offset:26112
	ds_read_b128 v[152:155], v133 offset:26128
	ds_read2st64_b32 v[108:109], v134 offset0:166 offset1:167
	ds_read_b128 v[32:35], v133 offset:1280
	ds_read_b128 v[36:39], v133 offset:1296
	ds_read_b128 v[40:43], v133 offset:17664
	ds_read_b128 v[44:47], v133 offset:17680
	ds_read_b128 v[48:51], v133 offset:34048
	ds_read_b128 v[52:55], v133 offset:34064
	s_waitcnt lgkmcnt(11)
	v_fmac_f32_e32 v112, v184, v136
	v_fmac_f32_e32 v113, v185, v136
	v_fmac_f32_e32 v114, v186, v136
	v_fmac_f32_e32 v115, v187, v136
	v_fmac_f32_e32 v116, v188, v136
	v_fmac_f32_e32 v117, v189, v136
	v_fmac_f32_e32 v118, v190, v136
	v_fmac_f32_e32 v119, v191, v136
	v_fma_f32 v122, v122, v176, v112
	v_fma_f32 v123, v123, v177, v113
	v_fma_f32 v124, v124, v178, v114
	v_fma_f32 v125, v125, v179, v115
	v_fma_f32 v126, v126, v180, v116
	v_fma_f32 v127, v127, v181, v117
	v_fma_f32 v128, v128, v182, v118
	v_fma_f32 v129, v129, v183, v119
	v_mul_f32_e32 v136, v122, v158
	v_mul_f32_e32 v137, v192, v122
	v_fmac_f32_e32 v136, v123, v159
	v_fmac_f32_e32 v137, v123, v193
	v_fmac_f32_e32 v136, v124, v160
	v_fmac_f32_e32 v137, v124, v194
	v_fmac_f32_e32 v136, v125, v161
	v_fmac_f32_e32 v137, v125, v195
	v_fmac_f32_e32 v136, v126, v162
	v_fmac_f32_e32 v137, v126, v196
	v_fmac_f32_e32 v136, v127, v163
	v_fmac_f32_e32 v137, v127, v197
	v_fmac_f32_e32 v136, v128, v164
	v_fmac_f32_e32 v137, v128, v198
	v_fmac_f32_e32 v136, v129, v165
	v_fmac_f32_e32 v137, v129, v199
	v_mul_f32_e32 v112, v166, v107
	v_mul_f32_e32 v113, v167, v107
	v_add_f32_dpp v136, v136, v136 quad_perm:[1,0,3,2] row_mask:0xf bank_mask:0xf bound_ctrl:1
	v_mul_f32_e32 v114, v168, v107
	v_mul_f32_e32 v115, v169, v107
	v_add_f32_dpp v136, v136, v136 quad_perm:[2,3,0,1] row_mask:0xf bank_mask:0xf bound_ctrl:1
	v_mul_f32_e32 v116, v170, v107
	v_mul_f32_e32 v117, v171, v107
	v_add_f32_dpp v136, v136, v136 row_half_mirror row_mask:0xf bank_mask:0xf bound_ctrl:1
	v_mul_f32_e32 v118, v172, v107
	v_mul_f32_e32 v119, v173, v107
	ds_read_b128 v[158:161], v133 offset:9984
	ds_read_b128 v[162:165], v133 offset:10000
	ds_read_b128 v[166:169], v133 offset:26368
	ds_read_b128 v[170:173], v133 offset:26384
	ds_read_b128 v[176:179], v133 offset:1536
	ds_read_b128 v[180:183], v133 offset:1552
	ds_read_b128 v[184:187], v133 offset:17920
	ds_read_b128 v[188:191], v133 offset:17936
	ds_read_b128 v[192:195], v133 offset:34304
	ds_read_b128 v[196:199], v133 offset:34320
	s_waitcnt lgkmcnt(10)
; template <int CTRL> __device__ __forceinline__ float dppf(float x) { return __builtin_bit_cast(float, __builtin_amdgcn_mov_dpp(__builtin_bit_cast(int, x), CTRL, 0xf, 0xf, true)); }
; #define LDOPS(s_) do { const float* p_ = bb + (s_) * 64; w4[(s_) % 3] = *(const f32x4*)(p_); a4[(s_) % 3] = *(const f32x4*)(p_ + 2048); b4[(s_) % 3] = *(const f32x4*)(p_ + 4096); k4[(s_) % 3] = *(const f32x4*)(p_ + 6144); \
;               r4[(s_) % 3] = *(const f32x4*)(p_ + 8192); vv[(s_) % 3] = vb[(s_) * 64]; } while (0)
; __device__ __forceinline__ void scan_block(unsigned char* shm, int sid, int half) {
;     ...
;           for (int s = 0; s < TS; ++s) {
;               const f32x4 a_ = a4[s % 3], w_ = w4[s % 3], b_ = b4[s % 3], k_ = k4[s % 3], r_ = r4[s % 3];
;               const float av[4] = {a_.x, a_.y, a_.z, a_.w}, wv[4] = {w_.x, w_.y, w_.z, w_.w}, bv[4] = {b_.x, b_.y, b_.z, b_.w}, kv[4] = {k_.x, k_.y, k_.z, k_.w}, rv[4] = {r_.x, r_.y, r_.z, r_.w};
;               const float v1 = vv[s % 3];
;               if (s + 2 < TS) LDOPS(s + 2);
;               float t = S[0] * av[0]; t = fmaf(S[1], av[1], t); t = fmaf(S[2], av[2], t); t = fmaf(S[3], av[3], t);
;               t += dppf<0xB1>(t); t += dppf<0x4E>(t); t += dppf<0x141>(t); t += dppf<0x140>(t);
; #pragma unroll
;               for (int q = 0; q < 4; ++q) S[q] = fmaf(S[q], wv[q], fmaf(bv[q], t, kv[q] * v1));
;               float u = S[0] * rv[0]; u = fmaf(S[1], rv[1], u); u = fmaf(S[2], rv[2], u); u = fmaf(S[3], rv[3], u);
;               u += dppf<0xB1>(u); u += dppf<0x4E>(u); u += dppf<0x141>(u); u += dppf<0x140>(u);
;               ys[s * 32] = u;
;           }
	v_fmac_f32_e32 v112, v40, v136
	v_fmac_f32_e32 v113, v41, v136
	v_fmac_f32_e32 v114, v42, v136
	v_fmac_f32_e32 v115, v43, v136
	v_fmac_f32_e32 v116, v44, v136
	v_fmac_f32_e32 v117, v45, v136
	v_fmac_f32_e32 v118, v46, v136
	v_fmac_f32_e32 v119, v47, v136
	v_fma_f32 v122, v122, v32, v112
	v_fma_f32 v123, v123, v33, v113
	v_fma_f32 v124, v124, v34, v114
	v_fma_f32 v125, v125, v35, v115
	v_fma_f32 v126, v126, v36, v116
	v_fma_f32 v127, v127, v37, v117
	v_fma_f32 v128, v128, v38, v118
	v_fma_f32 v129, v129, v39, v119
	v_mul_f32_e32 v136, v122, v140
	v_mul_f32_e32 v138, v48, v122
	v_fmac_f32_e32 v136, v123, v141
	v_fmac_f32_e32 v138, v123, v49
	v_fmac_f32_e32 v136, v124, v142
	v_fmac_f32_e32 v138, v124, v50
	v_fmac_f32_e32 v136, v125, v143
	v_fmac_f32_e32 v138, v125, v51
	v_fmac_f32_e32 v136, v126, v144
	v_fmac_f32_e32 v138, v126, v52
	v_fmac_f32_e32 v136, v127, v145
	v_fmac_f32_e32 v138, v127, v53
	v_fmac_f32_e32 v136, v128, v146
	v_fmac_f32_e32 v138, v128, v54
	v_fmac_f32_e32 v136, v129, v147
	v_fmac_f32_e32 v138, v129, v55
	v_mul_f32_e32 v112, v148, v108
	v_mul_f32_e32 v113, v149, v108
	v_add_f32_dpp v136, v136, v136 quad_perm:[1,0,3,2] row_mask:0xf bank_mask:0xf bound_ctrl:1
	v_add_f32_dpp v139, v137, v137 row_half_mirror row_mask:0xf bank_mask:0xf bound_ctrl:1
	v_add_f32_dpp v139, v138, v138 row_half_mirror row_mask:0xf bank_mask:0xa
	v_add_f32_dpp v136, v136, v136 quad_perm:[2,3,0,1] row_mask:0xf bank_mask:0xf bound_ctrl:1
	v_mul_f32_e32 v114, v150, v108
	v_mul_f32_e32 v115, v151, v108
	v_add_f32_dpp v139, v139, v139 quad_perm:[2,3,0,1] row_mask:0xf bank_mask:0xf bound_ctrl:1
	v_add_f32_dpp v136, v136, v136 row_half_mirror row_mask:0xf bank_mask:0xf bound_ctrl:1
	v_mul_f32_e32 v116, v152, v108
	v_mul_f32_e32 v117, v153, v108
	v_add_f32_dpp v139, v139, v139 quad_perm:[1,0,3,2] row_mask:0xf bank_mask:0xf bound_ctrl:1
	v_mul_f32_e32 v118, v154, v108
	v_mul_f32_e32 v119, v155, v108
	ds_write_b32 v135, v139 offset:512
	ds_read_b128 v[140:143], v133 offset:10240
	ds_read_b128 v[144:147], v133 offset:10256
	ds_read_b128 v[148:151], v133 offset:26624
	ds_read_b128 v[152:155], v133 offset:26640
	ds_read2st64_b32 v[106:107], v134 offset0:168 offset1:169
	ds_read_b128 v[32:35], v133 offset:1792
	ds_read_b128 v[36:39], v133 offset:1808
	ds_read_b128 v[40:43], v133 offset:18176
	ds_read_b128 v[44:47], v133 offset:18192
	ds_read_b128 v[48:51], v133 offset:34560
	ds_read_b128 v[52:55], v133 offset:34576
	s_waitcnt lgkmcnt(11)
	v_fmac_f32_e32 v112, v184, v136
	v_fmac_f32_e32 v113, v185, v136
	v_fmac_f32_e32 v114, v186, v136
	v_fmac_f32_e32 v115, v187, v136
	v_fmac_f32_e32 v116, v188, v136
	v_fmac_f32_e32 v117, v189, v136
	v_fmac_f32_e32 v118, v190, v136
	v_fmac_f32_e32 v119, v191, v136
	v_fma_f32 v122, v122, v176, v112
	v_fma_f32 v123, v123, v177, v113
	v_fma_f32 v124, v124, v178, v114
	v_fma_f32 v125, v125, v179, v115
	v_fma_f32 v126, v126, v180, v116
	v_fma_f32 v127, v127, v181, v117
	v_fma_f32 v128, v128, v182, v118
	v_fma_f32 v129, v129, v183, v119
	v_mul_f32_e32 v136, v122, v158
	v_mul_f32_e32 v137, v192, v122
	v_fmac_f32_e32 v136, v123, v159
	v_fmac_f32_e32 v137, v123, v193
	v_fmac_f32_e32 v136, v124, v160
	v_fmac_f32_e32 v137, v124, v194
	v_fmac_f32_e32 v136, v125, v161
	v_fmac_f32_e32 v137, v125, v195
	v_fmac_f32_e32 v136, v126, v162
	v_fmac_f32_e32 v137, v126, v196
	v_fmac_f32_e32 v136, v127, v163
	v_fmac_f32_e32 v137, v127, v197
	v_fmac_f32_e32 v136, v128, v164
	v_fmac_f32_e32 v137, v128, v198
	v_fmac_f32_e32 v136, v129, v165
	v_fmac_f32_e32 v137, v129, v199
	v_mul_f32_e32 v112, v166, v109
	v_mul_f32_e32 v113, v167, v109
	v_add_f32_dpp v136, v136, v136 quad_perm:[1,0,3,2] row_mask:0xf bank_mask:0xf bound_ctrl:1
	v_mul_f32_e32 v114, v168, v109
	v_mul_f32_e32 v115, v169, v109
	v_add_f32_dpp v136, v136, v136 quad_perm:[2,3,0,1] row_mask:0xf bank_mask:0xf bound_ctrl:1
	v_mul_f32_e32 v116, v170, v109
	v_mul_f32_e32 v117, v171, v109
	v_add_f32_dpp v136, v136, v136 row_half_mirror row_mask:0xf bank_mask:0xf bound_ctrl:1
	v_mul_f32_e32 v118, v172, v109
	v_mul_f32_e32 v119, v173, v109
	ds_read_b128 v[158:161], v133 offset:10496
	ds_read_b128 v[162:165], v133 offset:10512
	ds_read_b128 v[166:169], v133 offset:26880
	ds_read_b128 v[170:173], v133 offset:26896
	ds_read_b128 v[176:179], v133 offset:2048
	ds_read_b128 v[180:183], v133 offset:2064
	ds_read_b128 v[184:187], v133 offset:18432
	ds_read_b128 v[188:191], v133 offset:18448
	ds_read_b128 v[192:195], v133 offset:34816
	ds_read_b128 v[196:199], v133 offset:34832
	s_waitcnt lgkmcnt(10)
; template <int CTRL> __device__ __forceinline__ float dppf(float x) { return __builtin_bit_cast(float, __builtin_amdgcn_mov_dpp(__builtin_bit_cast(int, x), CTRL, 0xf, 0xf, true)); }
; #define LDOPS(s_) do { const float* p_ = bb + (s_) * 64; w4[(s_) % 3] = *(const f32x4*)(p_); a4[(s_) % 3] = *(const f32x4*)(p_ + 2048); b4[(s_) % 3] = *(const f32x4*)(p_ + 4096); k4[(s_) % 3] = *(const f32x4*)(p_ + 6144); \
;               r4[(s_) % 3] = *(const f32x4*)(p_ + 8192); vv[(s_) % 3] = vb[(s_) * 64]; } while (0)
; __device__ __forceinline__ void scan_block(unsigned char* shm, int sid, int half) {
;     ...
;           for (int s = 0; s < TS; ++s) {
;               const f32x4 a_ = a4[s % 3], w_ = w4[s % 3], b_ = b4[s % 3], k_ = k4[s % 3], r_ = r4[s % 3];
;               const float av[4] = {a_.x, a_.y, a_.z, a_.w}, wv[4] = {w_.x, w_.y, w_.z, w_.w}, bv[4] = {b_.x, b_.y, b_.z, b_.w}, kv[4] = {k_.x, k_.y, k_.z, k_.w}, rv[4] = {r_.x, r_.y, r_.z, r_.w};
;               const float v1 = vv[s % 3];
;               if (s + 2 < TS) LDOPS(s + 2);
;               float t = S[0] * av[0]; t = fmaf(S[1], av[1], t); t = fmaf(S[2], av[2], t); t = fmaf(S[3], av[3], t);
;               t += dppf<0xB1>(t); t += dppf<0x4E>(t); t += dppf<0x141>(t); t += dppf<0x140>(t);
; #pragma unroll
;               for (int q = 0; q < 4; ++q) S[q] = fmaf(S[q], wv[q], fmaf(bv[q], t, kv[q] * v1));
;               float u = S[0] * rv[0]; u = fmaf(S[1], rv[1], u); u = fmaf(S[2], rv[2], u); u = fmaf(S[3], rv[3], u);
;               u += dppf<0xB1>(u); u += dppf<0x4E>(u); u += dppf<0x141>(u); u += dppf<0x140>(u);
;               ys[s * 32] = u;
;           }
	v_fmac_f32_e32 v112, v40, v136
	v_fmac_f32_e32 v113, v41, v136
	v_fmac_f32_e32 v114, v42, v136
	v_fmac_f32_e32 v115, v43, v136
	v_fmac_f32_e32 v116, v44, v136
	v_fmac_f32_e32 v117, v45, v136
	v_fmac_f32_e32 v118, v46, v136
	v_fmac_f32_e32 v119, v47, v136
	v_fma_f32 v122, v122, v32, v112
	v_fma_f32 v123, v123, v33, v113
	v_fma_f32 v124, v124, v34, v114
	v_fma_f32 v125, v125, v35, v115
	v_fma_f32 v126, v126, v36, v116
	v_fma_f32 v127, v127, v37, v117
	v_fma_f32 v128, v128, v38, v118
	v_fma_f32 v129, v129, v39, v119
	v_mul_f32_e32 v136, v122, v140
	v_mul_f32_e32 v138, v48, v122
	v_fmac_f32_e32 v136, v123, v141
	v_fmac_f32_e32 v138, v123, v49
	v_fmac_f32_e32 v136, v124, v142
	v_fmac_f32_e32 v138, v124, v50
	v_fmac_f32_e32 v136, v125, v143
	v_fmac_f32_e32 v138, v125, v51
	v_fmac_f32_e32 v136, v126, v144
	v_fmac_f32_e32 v138, v126, v52
	v_fmac_f32_e32 v136, v127, v145
	v_fmac_f32_e32 v138, v127, v53
	v_fmac_f32_e32 v136, v128, v146
	v_fmac_f32_e32 v138, v128, v54
	v_fmac_f32_e32 v136, v129, v147
	v_fmac_f32_e32 v138, v129, v55
	v_mul_f32_e32 v112, v148, v106
	v_mul_f32_e32 v113, v149, v106
	v_add_f32_dpp v136, v136, v136 quad_perm:[1,0,3,2] row_mask:0xf bank_mask:0xf bound_ctrl:1
	v_add_f32_dpp v139, v137, v137 row_half_mirror row_mask:0xf bank_mask:0xf bound_ctrl:1
	v_add_f32_dpp v139, v138, v138 row_half_mirror row_mask:0xf bank_mask:0xa
	v_add_f32_dpp v136, v136, v136 quad_perm:[2,3,0,1] row_mask:0xf bank_mask:0xf bound_ctrl:1
	v_mul_f32_e32 v114, v150, v106
	v_mul_f32_e32 v115, v151, v106
	v_add_f32_dpp v139, v139, v139 quad_perm:[2,3,0,1] row_mask:0xf bank_mask:0xf bound_ctrl:1
	v_add_f32_dpp v136, v136, v136 row_half_mirror row_mask:0xf bank_mask:0xf bound_ctrl:1
	v_mul_f32_e32 v116, v152, v106
	v_mul_f32_e32 v117, v153, v106
	v_add_f32_dpp v139, v139, v139 quad_perm:[1,0,3,2] row_mask:0xf bank_mask:0xf bound_ctrl:1
	v_mul_f32_e32 v118, v154, v106
	v_mul_f32_e32 v119, v155, v106
	ds_write_b32 v135, v139 offset:768
	ds_read_b128 v[140:143], v133 offset:10752
	ds_read_b128 v[144:147], v133 offset:10768
	ds_read_b128 v[148:151], v133 offset:27136
	ds_read_b128 v[152:155], v133 offset:27152
	ds_read2st64_b32 v[108:109], v134 offset0:170 offset1:171
	ds_read_b128 v[32:35], v133 offset:2304
	ds_read_b128 v[36:39], v133 offset:2320
	ds_read_b128 v[40:43], v133 offset:18688
	ds_read_b128 v[44:47], v133 offset:18704
	ds_read_b128 v[48:51], v133 offset:35072
	ds_read_b128 v[52:55], v133 offset:35088
	s_waitcnt lgkmcnt(11)
	v_fmac_f32_e32 v112, v184, v136
	v_fmac_f32_e32 v113, v185, v136
	v_fmac_f32_e32 v114, v186, v136
	v_fmac_f32_e32 v115, v187, v136
	v_fmac_f32_e32 v116, v188, v136
	v_fmac_f32_e32 v117, v189, v136
	v_fmac_f32_e32 v118, v190, v136
	v_fmac_f32_e32 v119, v191, v136
	v_fma_f32 v122, v122, v176, v112
	v_fma_f32 v123, v123, v177, v113
	v_fma_f32 v124, v124, v178, v114
	v_fma_f32 v125, v125, v179, v115
	v_fma_f32 v126, v126, v180, v116
	v_fma_f32 v127, v127, v181, v117
	v_fma_f32 v128, v128, v182, v118
	v_fma_f32 v129, v129, v183, v119
	v_mul_f32_e32 v136, v122, v158
	v_mul_f32_e32 v137, v192, v122
	v_fmac_f32_e32 v136, v123, v159
	v_fmac_f32_e32 v137, v123, v193
	v_fmac_f32_e32 v136, v124, v160
	v_fmac_f32_e32 v137, v124, v194
	v_fmac_f32_e32 v136, v125, v161
	v_fmac_f32_e32 v137, v125, v195
	v_fmac_f32_e32 v136, v126, v162
	v_fmac_f32_e32 v137, v126, v196
	v_fmac_f32_e32 v136, v127, v163
	v_fmac_f32_e32 v137, v127, v197
	v_fmac_f32_e32 v136, v128, v164
	v_fmac_f32_e32 v137, v128, v198
	v_fmac_f32_e32 v136, v129, v165
	v_fmac_f32_e32 v137, v129, v199
	v_mul_f32_e32 v112, v166, v107
	v_mul_f32_e32 v113, v167, v107
	v_add_f32_dpp v136, v136, v136 quad_perm:[1,0,3,2] row_mask:0xf bank_mask:0xf bound_ctrl:1
	v_mul_f32_e32 v114, v168, v107
	v_mul_f32_e32 v115, v169, v107
	v_add_f32_dpp v136, v136, v136 quad_perm:[2,3,0,1] row_mask:0xf bank_mask:0xf bound_ctrl:1
	v_mul_f32_e32 v116, v170, v107
	v_mul_f32_e32 v117, v171, v107
	v_add_f32_dpp v136, v136, v136 row_half_mirror row_mask:0xf bank_mask:0xf bound_ctrl:1
	v_mul_f32_e32 v118, v172, v107
	v_mul_f32_e32 v119, v173, v107
	ds_read_b128 v[158:161], v133 offset:11008
	ds_read_b128 v[162:165], v133 offset:11024
	ds_read_b128 v[166:169], v133 offset:27392
	ds_read_b128 v[170:173], v133 offset:27408
	ds_read_b128 v[176:179], v133 offset:2560
	ds_read_b128 v[180:183], v133 offset:2576
	ds_read_b128 v[184:187], v133 offset:18944
	ds_read_b128 v[188:191], v133 offset:18960
	ds_read_b128 v[192:195], v133 offset:35328
	ds_read_b128 v[196:199], v133 offset:35344
	s_waitcnt lgkmcnt(10)
; template <int CTRL> __device__ __forceinline__ float dppf(float x) { return __builtin_bit_cast(float, __builtin_amdgcn_mov_dpp(__builtin_bit_cast(int, x), CTRL, 0xf, 0xf, true)); }
; #define LDOPS(s_) do { const float* p_ = bb + (s_) * 64; w4[(s_) % 3] = *(const f32x4*)(p_); a4[(s_) % 3] = *(const f32x4*)(p_ + 2048); b4[(s_) % 3] = *(const f32x4*)(p_ + 4096); k4[(s_) % 3] = *(const f32x4*)(p_ + 6144); \
;               r4[(s_) % 3] = *(const f32x4*)(p_ + 8192); vv[(s_) % 3] = vb[(s_) * 64]; } while (0)
; __device__ __forceinline__ void scan_block(unsigned char* shm, int sid, int half) {
;     ...
;           for (int s = 0; s < TS; ++s) {
;               const f32x4 a_ = a4[s % 3], w_ = w4[s % 3], b_ = b4[s % 3], k_ = k4[s % 3], r_ = r4[s % 3];
;               const float av[4] = {a_.x, a_.y, a_.z, a_.w}, wv[4] = {w_.x, w_.y, w_.z, w_.w}, bv[4] = {b_.x, b_.y, b_.z, b_.w}, kv[4] = {k_.x, k_.y, k_.z, k_.w}, rv[4] = {r_.x, r_.y, r_.z, r_.w};
;               const float v1 = vv[s % 3];
;               if (s + 2 < TS) LDOPS(s + 2);
;               float t = S[0] * av[0]; t = fmaf(S[1], av[1], t); t = fmaf(S[2], av[2], t); t = fmaf(S[3], av[3], t);
;               t += dppf<0xB1>(t); t += dppf<0x4E>(t); t += dppf<0x141>(t); t += dppf<0x140>(t);
; #pragma unroll
;               for (int q = 0; q < 4; ++q) S[q] = fmaf(S[q], wv[q], fmaf(bv[q], t, kv[q] * v1));
;               float u = S[0] * rv[0]; u = fmaf(S[1], rv[1], u); u = fmaf(S[2], rv[2], u); u = fmaf(S[3], rv[3], u);
;               u += dppf<0xB1>(u); u += dppf<0x4E>(u); u += dppf<0x141>(u); u += dppf<0x140>(u);
;               ys[s * 32] = u;
;           }
	v_fmac_f32_e32 v112, v40, v136
	v_fmac_f32_e32 v113, v41, v136
	v_fmac_f32_e32 v114, v42, v136
	v_fmac_f32_e32 v115, v43, v136
	v_fmac_f32_e32 v116, v44, v136
	v_fmac_f32_e32 v117, v45, v136
	v_fmac_f32_e32 v118, v46, v136
	v_fmac_f32_e32 v119, v47, v136
	v_fma_f32 v122, v122, v32, v112
	v_fma_f32 v123, v123, v33, v113
	v_fma_f32 v124, v124, v34, v114
	v_fma_f32 v125, v125, v35, v115
	v_fma_f32 v126, v126, v36, v116
	v_fma_f32 v127, v127, v37, v117
	v_fma_f32 v128, v128, v38, v118
	v_fma_f32 v129, v129, v39, v119
	v_mul_f32_e32 v136, v122, v140
	v_mul_f32_e32 v138, v48, v122
	v_fmac_f32_e32 v136, v123, v141
	v_fmac_f32_e32 v138, v123, v49
	v_fmac_f32_e32 v136, v124, v142
	v_fmac_f32_e32 v138, v124, v50
	v_fmac_f32_e32 v136, v125, v143
	v_fmac_f32_e32 v138, v125, v51
	v_fmac_f32_e32 v136, v126, v144
	v_fmac_f32_e32 v138, v126, v52
	v_fmac_f32_e32 v136, v127, v145
	v_fmac_f32_e32 v138, v127, v53
	v_fmac_f32_e32 v136, v128, v146
	v_fmac_f32_e32 v138, v128, v54
	v_fmac_f32_e32 v136, v129, v147
	v_fmac_f32_e32 v138, v129, v55
	v_mul_f32_e32 v112, v148, v108
	v_mul_f32_e32 v113, v149, v108
	v_add_f32_dpp v136, v136, v136 quad_perm:[1,0,3,2] row_mask:0xf bank_mask:0xf bound_ctrl:1
	v_add_f32_dpp v139, v137, v137 row_half_mirror row_mask:0xf bank_mask:0xf bound_ctrl:1
	v_add_f32_dpp v139, v138, v138 row_half_mirror row_mask:0xf bank_mask:0xa
	v_add_f32_dpp v136, v136, v136 quad_perm:[2,3,0,1] row_mask:0xf bank_mask:0xf bound_ctrl:1
	v_mul_f32_e32 v114, v150, v108
	v_mul_f32_e32 v115, v151, v108
	v_add_f32_dpp v139, v139, v139 quad_perm:[2,3,0,1] row_mask:0xf bank_mask:0xf bound_ctrl:1
	v_add_f32_dpp v136, v136, v136 row_half_mirror row_mask:0xf bank_mask:0xf bound_ctrl:1
	v_mul_f32_e32 v116, v152, v108
	v_mul_f32_e32 v117, v153, v108
	v_add_f32_dpp v139, v139, v139 quad_perm:[1,0,3,2] row_mask:0xf bank_mask:0xf bound_ctrl:1
	v_mul_f32_e32 v118, v154, v108
	v_mul_f32_e32 v119, v155, v108
	ds_write_b32 v135, v139 offset:1024
	ds_read_b128 v[140:143], v133 offset:11264
	ds_read_b128 v[144:147], v133 offset:11280
	ds_read_b128 v[148:151], v133 offset:27648
	ds_read_b128 v[152:155], v133 offset:27664
	ds_read2st64_b32 v[106:107], v134 offset0:172 offset1:173
	ds_read_b128 v[32:35], v133 offset:2816
	ds_read_b128 v[36:39], v133 offset:2832
	ds_read_b128 v[40:43], v133 offset:19200
	ds_read_b128 v[44:47], v133 offset:19216
	ds_read_b128 v[48:51], v133 offset:35584
	ds_read_b128 v[52:55], v133 offset:35600
	s_waitcnt lgkmcnt(11)
	v_fmac_f32_e32 v112, v184, v136
	v_fmac_f32_e32 v113, v185, v136
	v_fmac_f32_e32 v114, v186, v136
	v_fmac_f32_e32 v115, v187, v136
	v_fmac_f32_e32 v116, v188, v136
	v_fmac_f32_e32 v117, v189, v136
	v_fmac_f32_e32 v118, v190, v136
	v_fmac_f32_e32 v119, v191, v136
	v_fma_f32 v122, v122, v176, v112
	v_fma_f32 v123, v123, v177, v113
	v_fma_f32 v124, v124, v178, v114
	v_fma_f32 v125, v125, v179, v115
	v_fma_f32 v126, v126, v180, v116
	v_fma_f32 v127, v127, v181, v117
	v_fma_f32 v128, v128, v182, v118
	v_fma_f32 v129, v129, v183, v119
	v_mul_f32_e32 v136, v122, v158
	v_mul_f32_e32 v137, v192, v122
	v_fmac_f32_e32 v136, v123, v159
	v_fmac_f32_e32 v137, v123, v193
	v_fmac_f32_e32 v136, v124, v160
	v_fmac_f32_e32 v137, v124, v194
	v_fmac_f32_e32 v136, v125, v161
	v_fmac_f32_e32 v137, v125, v195
	v_fmac_f32_e32 v136, v126, v162
	v_fmac_f32_e32 v137, v126, v196
	v_fmac_f32_e32 v136, v127, v163
	v_fmac_f32_e32 v137, v127, v197
	v_fmac_f32_e32 v136, v128, v164
	v_fmac_f32_e32 v137, v128, v198
	v_fmac_f32_e32 v136, v129, v165
	v_fmac_f32_e32 v137, v129, v199
	v_mul_f32_e32 v112, v166, v109
	v_mul_f32_e32 v113, v167, v109
	v_add_f32_dpp v136, v136, v136 quad_perm:[1,0,3,2] row_mask:0xf bank_mask:0xf bound_ctrl:1
	v_mul_f32_e32 v114, v168, v109
	v_mul_f32_e32 v115, v169, v109
	v_add_f32_dpp v136, v136, v136 quad_perm:[2,3,0,1] row_mask:0xf bank_mask:0xf bound_ctrl:1
	v_mul_f32_e32 v116, v170, v109
	v_mul_f32_e32 v117, v171, v109
	v_add_f32_dpp v136, v136, v136 row_half_mirror row_mask:0xf bank_mask:0xf bound_ctrl:1
	v_mul_f32_e32 v118, v172, v109
	v_mul_f32_e32 v119, v173, v109
	ds_read_b128 v[158:161], v133 offset:11520
	ds_read_b128 v[162:165], v133 offset:11536
	ds_read_b128 v[166:169], v133 offset:27904
	ds_read_b128 v[170:173], v133 offset:27920
	ds_read_b128 v[176:179], v133 offset:3072
	ds_read_b128 v[180:183], v133 offset:3088
	ds_read_b128 v[184:187], v133 offset:19456
	ds_read_b128 v[188:191], v133 offset:19472
	ds_read_b128 v[192:195], v133 offset:35840
	ds_read_b128 v[196:199], v133 offset:35856
	s_waitcnt lgkmcnt(10)
; template <int CTRL> __device__ __forceinline__ float dppf(float x) { return __builtin_bit_cast(float, __builtin_amdgcn_mov_dpp(__builtin_bit_cast(int, x), CTRL, 0xf, 0xf, true)); }
; #define LDOPS(s_) do { const float* p_ = bb + (s_) * 64; w4[(s_) % 3] = *(const f32x4*)(p_); a4[(s_) % 3] = *(const f32x4*)(p_ + 2048); b4[(s_) % 3] = *(const f32x4*)(p_ + 4096); k4[(s_) % 3] = *(const f32x4*)(p_ + 6144); \
;               r4[(s_) % 3] = *(const f32x4*)(p_ + 8192); vv[(s_) % 3] = vb[(s_) * 64]; } while (0)
; __device__ __forceinline__ void scan_block(unsigned char* shm, int sid, int half) {
;     ...
;           for (int s = 0; s < TS; ++s) {
;               const f32x4 a_ = a4[s % 3], w_ = w4[s % 3], b_ = b4[s % 3], k_ = k4[s % 3], r_ = r4[s % 3];
;               const float av[4] = {a_.x, a_.y, a_.z, a_.w}, wv[4] = {w_.x, w_.y, w_.z, w_.w}, bv[4] = {b_.x, b_.y, b_.z, b_.w}, kv[4] = {k_.x, k_.y, k_.z, k_.w}, rv[4] = {r_.x, r_.y, r_.z, r_.w};
;               const float v1 = vv[s % 3];
;               if (s + 2 < TS) LDOPS(s + 2);
;               float t = S[0] * av[0]; t = fmaf(S[1], av[1], t); t = fmaf(S[2], av[2], t); t = fmaf(S[3], av[3], t);
;               t += dppf<0xB1>(t); t += dppf<0x4E>(t); t += dppf<0x141>(t); t += dppf<0x140>(t);
; #pragma unroll
;               for (int q = 0; q < 4; ++q) S[q] = fmaf(S[q], wv[q], fmaf(bv[q], t, kv[q] * v1));
;               float u = S[0] * rv[0]; u = fmaf(S[1], rv[1], u); u = fmaf(S[2], rv[2], u); u = fmaf(S[3], rv[3], u);
;               u += dppf<0xB1>(u); u += dppf<0x4E>(u); u += dppf<0x141>(u); u += dppf<0x140>(u);
;               ys[s * 32] = u;
;           }
	v_fmac_f32_e32 v112, v40, v136
	v_fmac_f32_e32 v113, v41, v136
	v_fmac_f32_e32 v114, v42, v136
	v_fmac_f32_e32 v115, v43, v136
	v_fmac_f32_e32 v116, v44, v136
	v_fmac_f32_e32 v117, v45, v136
	v_fmac_f32_e32 v118, v46, v136
	v_fmac_f32_e32 v119, v47, v136
	v_fma_f32 v122, v122, v32, v112
	v_fma_f32 v123, v123, v33, v113
	v_fma_f32 v124, v124, v34, v114
	v_fma_f32 v125, v125, v35, v115
	v_fma_f32 v126, v126, v36, v116
	v_fma_f32 v127, v127, v37, v117
	v_fma_f32 v128, v128, v38, v118
	v_fma_f32 v129, v129, v39, v119
	v_mul_f32_e32 v136, v122, v140
	v_mul_f32_e32 v138, v48, v122
	v_fmac_f32_e32 v136, v123, v141
	v_fmac_f32_e32 v138, v123, v49
	v_fmac_f32_e32 v136, v124, v142
	v_fmac_f32_e32 v138, v124, v50
	v_fmac_f32_e32 v136, v125, v143
	v_fmac_f32_e32 v138, v125, v51
	v_fmac_f32_e32 v136, v126, v144
	v_fmac_f32_e32 v138, v126, v52
	v_fmac_f32_e32 v136, v127, v145
	v_fmac_f32_e32 v138, v127, v53
	v_fmac_f32_e32 v136, v128, v146
	v_fmac_f32_e32 v138, v128, v54
	v_fmac_f32_e32 v136, v129, v147
	v_fmac_f32_e32 v138, v129, v55
	v_mul_f32_e32 v112, v148, v106
	v_mul_f32_e32 v113, v149, v106
	v_add_f32_dpp v136, v136, v136 quad_perm:[1,0,3,2] row_mask:0xf bank_mask:0xf bound_ctrl:1
	v_add_f32_dpp v139, v137, v137 row_half_mirror row_mask:0xf bank_mask:0xf bound_ctrl:1
	v_add_f32_dpp v139, v138, v138 row_half_mirror row_mask:0xf bank_mask:0xa
	v_add_f32_dpp v136, v136, v136 quad_perm:[2,3,0,1] row_mask:0xf bank_mask:0xf bound_ctrl:1
	v_mul_f32_e32 v114, v150, v106
	v_mul_f32_e32 v115, v151, v106
	v_add_f32_dpp v139, v139, v139 quad_perm:[2,3,0,1] row_mask:0xf bank_mask:0xf bound_ctrl:1
	v_add_f32_dpp v136, v136, v136 row_half_mirror row_mask:0xf bank_mask:0xf bound_ctrl:1
	v_mul_f32_e32 v116, v152, v106
	v_mul_f32_e32 v117, v153, v106
	v_add_f32_dpp v139, v139, v139 quad_perm:[1,0,3,2] row_mask:0xf bank_mask:0xf bound_ctrl:1
	v_mul_f32_e32 v118, v154, v106
	v_mul_f32_e32 v119, v155, v106
	ds_write_b32 v135, v139 offset:1280
	ds_read_b128 v[140:143], v133 offset:11776
	ds_read_b128 v[144:147], v133 offset:11792
	ds_read_b128 v[148:151], v133 offset:28160
	ds_read_b128 v[152:155], v133 offset:28176
	ds_read2st64_b32 v[108:109], v134 offset0:174 offset1:175
	ds_read_b128 v[32:35], v133 offset:3328
	ds_read_b128 v[36:39], v133 offset:3344
	ds_read_b128 v[40:43], v133 offset:19712
	ds_read_b128 v[44:47], v133 offset:19728
	ds_read_b128 v[48:51], v133 offset:36096
	ds_read_b128 v[52:55], v133 offset:36112
	s_waitcnt lgkmcnt(11)
	v_fmac_f32_e32 v112, v184, v136
	v_fmac_f32_e32 v113, v185, v136
	v_fmac_f32_e32 v114, v186, v136
	v_fmac_f32_e32 v115, v187, v136
	v_fmac_f32_e32 v116, v188, v136
	v_fmac_f32_e32 v117, v189, v136
	v_fmac_f32_e32 v118, v190, v136
	v_fmac_f32_e32 v119, v191, v136
	v_fma_f32 v122, v122, v176, v112
	v_fma_f32 v123, v123, v177, v113
	v_fma_f32 v124, v124, v178, v114
	v_fma_f32 v125, v125, v179, v115
	v_fma_f32 v126, v126, v180, v116
	v_fma_f32 v127, v127, v181, v117
	v_fma_f32 v128, v128, v182, v118
	v_fma_f32 v129, v129, v183, v119
	v_mul_f32_e32 v136, v122, v158
	v_mul_f32_e32 v137, v192, v122
	v_fmac_f32_e32 v136, v123, v159
	v_fmac_f32_e32 v137, v123, v193
	v_fmac_f32_e32 v136, v124, v160
	v_fmac_f32_e32 v137, v124, v194
	v_fmac_f32_e32 v136, v125, v161
	v_fmac_f32_e32 v137, v125, v195
	v_fmac_f32_e32 v136, v126, v162
	v_fmac_f32_e32 v137, v126, v196
	v_fmac_f32_e32 v136, v127, v163
	v_fmac_f32_e32 v137, v127, v197
	v_fmac_f32_e32 v136, v128, v164
	v_fmac_f32_e32 v137, v128, v198
	v_fmac_f32_e32 v136, v129, v165
	v_fmac_f32_e32 v137, v129, v199
	v_mul_f32_e32 v112, v166, v107
	v_mul_f32_e32 v113, v167, v107
	v_add_f32_dpp v136, v136, v136 quad_perm:[1,0,3,2] row_mask:0xf bank_mask:0xf bound_ctrl:1
	v_mul_f32_e32 v114, v168, v107
	v_mul_f32_e32 v115, v169, v107
	v_add_f32_dpp v136, v136, v136 quad_perm:[2,3,0,1] row_mask:0xf bank_mask:0xf bound_ctrl:1
	v_mul_f32_e32 v116, v170, v107
	v_mul_f32_e32 v117, v171, v107
	v_add_f32_dpp v136, v136, v136 row_half_mirror row_mask:0xf bank_mask:0xf bound_ctrl:1
	v_mul_f32_e32 v118, v172, v107
	v_mul_f32_e32 v119, v173, v107
	ds_read_b128 v[158:161], v133 offset:12032
	ds_read_b128 v[162:165], v133 offset:12048
	ds_read_b128 v[166:169], v133 offset:28416
	ds_read_b128 v[170:173], v133 offset:28432
	ds_read_b128 v[176:179], v133 offset:3584
	ds_read_b128 v[180:183], v133 offset:3600
	ds_read_b128 v[184:187], v133 offset:19968
	ds_read_b128 v[188:191], v133 offset:19984
	ds_read_b128 v[192:195], v133 offset:36352
	ds_read_b128 v[196:199], v133 offset:36368
	s_waitcnt lgkmcnt(10)
; template <int CTRL> __device__ __forceinline__ float dppf(float x) { return __builtin_bit_cast(float, __builtin_amdgcn_mov_dpp(__builtin_bit_cast(int, x), CTRL, 0xf, 0xf, true)); }
; #define LDOPS(s_) do { const float* p_ = bb + (s_) * 64; w4[(s_) % 3] = *(const f32x4*)(p_); a4[(s_) % 3] = *(const f32x4*)(p_ + 2048); b4[(s_) % 3] = *(const f32x4*)(p_ + 4096); k4[(s_) % 3] = *(const f32x4*)(p_ + 6144); \
;               r4[(s_) % 3] = *(const f32x4*)(p_ + 8192); vv[(s_) % 3] = vb[(s_) * 64]; } while (0)
; __device__ __forceinline__ void scan_block(unsigned char* shm, int sid, int half) {
;     ...
;           for (int s = 0; s < TS; ++s) {
;               const f32x4 a_ = a4[s % 3], w_ = w4[s % 3], b_ = b4[s % 3], k_ = k4[s % 3], r_ = r4[s % 3];
;               const float av[4] = {a_.x, a_.y, a_.z, a_.w}, wv[4] = {w_.x, w_.y, w_.z, w_.w}, bv[4] = {b_.x, b_.y, b_.z, b_.w}, kv[4] = {k_.x, k_.y, k_.z, k_.w}, rv[4] = {r_.x, r_.y, r_.z, r_.w};
;               const float v1 = vv[s % 3];
;               if (s + 2 < TS) LDOPS(s + 2);
;               float t = S[0] * av[0]; t = fmaf(S[1], av[1], t); t = fmaf(S[2], av[2], t); t = fmaf(S[3], av[3], t);
;               t += dppf<0xB1>(t); t += dppf<0x4E>(t); t += dppf<0x141>(t); t += dppf<0x140>(t);
; #pragma unroll
;               for (int q = 0; q < 4; ++q) S[q] = fmaf(S[q], wv[q], fmaf(bv[q], t, kv[q] * v1));
;               float u = S[0] * rv[0]; u = fmaf(S[1], rv[1], u); u = fmaf(S[2], rv[2], u); u = fmaf(S[3], rv[3], u);
;               u += dppf<0xB1>(u); u += dppf<0x4E>(u); u += dppf<0x141>(u); u += dppf<0x140>(u);
;               ys[s * 32] = u;
;           }
	v_fmac_f32_e32 v112, v40, v136
	v_fmac_f32_e32 v113, v41, v136
	v_fmac_f32_e32 v114, v42, v136
	v_fmac_f32_e32 v115, v43, v136
	v_fmac_f32_e32 v116, v44, v136
	v_fmac_f32_e32 v117, v45, v136
	v_fmac_f32_e32 v118, v46, v136
	v_fmac_f32_e32 v119, v47, v136
	v_fma_f32 v122, v122, v32, v112
	v_fma_f32 v123, v123, v33, v113
	v_fma_f32 v124, v124, v34, v114
	v_fma_f32 v125, v125, v35, v115
	v_fma_f32 v126, v126, v36, v116
	v_fma_f32 v127, v127, v37, v117
	v_fma_f32 v128, v128, v38, v118
	v_fma_f32 v129, v129, v39, v119
	v_mul_f32_e32 v136, v122, v140
	v_mul_f32_e32 v138, v48, v122
	v_fmac_f32_e32 v136, v123, v141
	v_fmac_f32_e32 v138, v123, v49
	v_fmac_f32_e32 v136, v124, v142
	v_fmac_f32_e32 v138, v124, v50
	v_fmac_f32_e32 v136, v125, v143
	v_fmac_f32_e32 v138, v125, v51
	v_fmac_f32_e32 v136, v126, v144
	v_fmac_f32_e32 v138, v126, v52
	v_fmac_f32_e32 v136, v127, v145
	v_fmac_f32_e32 v138, v127, v53
	v_fmac_f32_e32 v136, v128, v146
	v_fmac_f32_e32 v138, v128, v54
	v_fmac_f32_e32 v136, v129, v147
	v_fmac_f32_e32 v138, v129, v55
	v_mul_f32_e32 v112, v148, v108
	v_mul_f32_e32 v113, v149, v108
	v_add_f32_dpp v136, v136, v136 quad_perm:[1,0,3,2] row_mask:0xf bank_mask:0xf bound_ctrl:1
	v_add_f32_dpp v139, v137, v137 row_half_mirror row_mask:0xf bank_mask:0xf bound_ctrl:1
	v_add_f32_dpp v139, v138, v138 row_half_mirror row_mask:0xf bank_mask:0xa
	v_add_f32_dpp v136, v136, v136 quad_perm:[2,3,0,1] row_mask:0xf bank_mask:0xf bound_ctrl:1
	v_mul_f32_e32 v114, v150, v108
	v_mul_f32_e32 v115, v151, v108
	v_add_f32_dpp v139, v139, v139 quad_perm:[2,3,0,1] row_mask:0xf bank_mask:0xf bound_ctrl:1
	v_add_f32_dpp v136, v136, v136 row_half_mirror row_mask:0xf bank_mask:0xf bound_ctrl:1
	v_mul_f32_e32 v116, v152, v108
	v_mul_f32_e32 v117, v153, v108
	v_add_f32_dpp v139, v139, v139 quad_perm:[1,0,3,2] row_mask:0xf bank_mask:0xf bound_ctrl:1
	v_mul_f32_e32 v118, v154, v108
	v_mul_f32_e32 v119, v155, v108
	ds_write_b32 v135, v139 offset:1536
	ds_read_b128 v[140:143], v133 offset:12288
	ds_read_b128 v[144:147], v133 offset:12304
	ds_read_b128 v[148:151], v133 offset:28672
	ds_read_b128 v[152:155], v133 offset:28688
	ds_read2st64_b32 v[106:107], v134 offset0:176 offset1:177
	ds_read_b128 v[32:35], v133 offset:3840
	ds_read_b128 v[36:39], v133 offset:3856
	ds_read_b128 v[40:43], v133 offset:20224
	ds_read_b128 v[44:47], v133 offset:20240
	ds_read_b128 v[48:51], v133 offset:36608
	ds_read_b128 v[52:55], v133 offset:36624
	s_waitcnt lgkmcnt(11)
	v_fmac_f32_e32 v112, v184, v136
	v_fmac_f32_e32 v113, v185, v136
	v_fmac_f32_e32 v114, v186, v136
	v_fmac_f32_e32 v115, v187, v136
	v_fmac_f32_e32 v116, v188, v136
	v_fmac_f32_e32 v117, v189, v136
	v_fmac_f32_e32 v118, v190, v136
	v_fmac_f32_e32 v119, v191, v136
	v_fma_f32 v122, v122, v176, v112
	v_fma_f32 v123, v123, v177, v113
	v_fma_f32 v124, v124, v178, v114
	v_fma_f32 v125, v125, v179, v115
	v_fma_f32 v126, v126, v180, v116
	v_fma_f32 v127, v127, v181, v117
	v_fma_f32 v128, v128, v182, v118
	v_fma_f32 v129, v129, v183, v119
	v_mul_f32_e32 v136, v122, v158
	v_mul_f32_e32 v137, v192, v122
	v_fmac_f32_e32 v136, v123, v159
	v_fmac_f32_e32 v137, v123, v193
	v_fmac_f32_e32 v136, v124, v160
	v_fmac_f32_e32 v137, v124, v194
	v_fmac_f32_e32 v136, v125, v161
	v_fmac_f32_e32 v137, v125, v195
	v_fmac_f32_e32 v136, v126, v162
	v_fmac_f32_e32 v137, v126, v196
	v_fmac_f32_e32 v136, v127, v163
	v_fmac_f32_e32 v137, v127, v197
	v_fmac_f32_e32 v136, v128, v164
	v_fmac_f32_e32 v137, v128, v198
	v_fmac_f32_e32 v136, v129, v165
	v_fmac_f32_e32 v137, v129, v199
	v_mul_f32_e32 v112, v166, v109
	v_mul_f32_e32 v113, v167, v109
	v_add_f32_dpp v136, v136, v136 quad_perm:[1,0,3,2] row_mask:0xf bank_mask:0xf bound_ctrl:1
	v_mul_f32_e32 v114, v168, v109
	v_mul_f32_e32 v115, v169, v109
	v_add_f32_dpp v136, v136, v136 quad_perm:[2,3,0,1] row_mask:0xf bank_mask:0xf bound_ctrl:1
	v_mul_f32_e32 v116, v170, v109
	v_mul_f32_e32 v117, v171, v109
	v_add_f32_dpp v136, v136, v136 row_half_mirror row_mask:0xf bank_mask:0xf bound_ctrl:1
	v_mul_f32_e32 v118, v172, v109
	v_mul_f32_e32 v119, v173, v109
	ds_read_b128 v[158:161], v133 offset:12544
	ds_read_b128 v[162:165], v133 offset:12560
	ds_read_b128 v[166:169], v133 offset:28928
	ds_read_b128 v[170:173], v133 offset:28944
	ds_read_b128 v[176:179], v133 offset:4096
	ds_read_b128 v[180:183], v133 offset:4112
	ds_read_b128 v[184:187], v133 offset:20480
	ds_read_b128 v[188:191], v133 offset:20496
	ds_read_b128 v[192:195], v133 offset:36864
	ds_read_b128 v[196:199], v133 offset:36880
	s_waitcnt lgkmcnt(10)
; template <int CTRL> __device__ __forceinline__ float dppf(float x) { return __builtin_bit_cast(float, __builtin_amdgcn_mov_dpp(__builtin_bit_cast(int, x), CTRL, 0xf, 0xf, true)); }
; #define LDOPS(s_) do { const float* p_ = bb + (s_) * 64; w4[(s_) % 3] = *(const f32x4*)(p_); a4[(s_) % 3] = *(const f32x4*)(p_ + 2048); b4[(s_) % 3] = *(const f32x4*)(p_ + 4096); k4[(s_) % 3] = *(const f32x4*)(p_ + 6144); \
;               r4[(s_) % 3] = *(const f32x4*)(p_ + 8192); vv[(s_) % 3] = vb[(s_) * 64]; } while (0)
; __device__ __forceinline__ void scan_block(unsigned char* shm, int sid, int half) {
;     ...
;           for (int s = 0; s < TS; ++s) {
;               const f32x4 a_ = a4[s % 3], w_ = w4[s % 3], b_ = b4[s % 3], k_ = k4[s % 3], r_ = r4[s % 3];
;               const float av[4] = {a_.x, a_.y, a_.z, a_.w}, wv[4] = {w_.x, w_.y, w_.z, w_.w}, bv[4] = {b_.x, b_.y, b_.z, b_.w}, kv[4] = {k_.x, k_.y, k_.z, k_.w}, rv[4] = {r_.x, r_.y, r_.z, r_.w};
;               const float v1 = vv[s % 3];
;               if (s + 2 < TS) LDOPS(s + 2);
;               float t = S[0] * av[0]; t = fmaf(S[1], av[1], t); t = fmaf(S[2], av[2], t); t = fmaf(S[3], av[3], t);
;               t += dppf<0xB1>(t); t += dppf<0x4E>(t); t += dppf<0x141>(t); t += dppf<0x140>(t);
; #pragma unroll
;               for (int q = 0; q < 4; ++q) S[q] = fmaf(S[q], wv[q], fmaf(bv[q], t, kv[q] * v1));
;               float u = S[0] * rv[0]; u = fmaf(S[1], rv[1], u); u = fmaf(S[2], rv[2], u); u = fmaf(S[3], rv[3], u);
;               u += dppf<0xB1>(u); u += dppf<0x4E>(u); u += dppf<0x141>(u); u += dppf<0x140>(u);
;               ys[s * 32] = u;
;           }
	v_fmac_f32_e32 v112, v40, v136
	v_fmac_f32_e32 v113, v41, v136
	v_fmac_f32_e32 v114, v42, v136
	v_fmac_f32_e32 v115, v43, v136
	v_fmac_f32_e32 v116, v44, v136
	v_fmac_f32_e32 v117, v45, v136
	v_fmac_f32_e32 v118, v46, v136
	v_fmac_f32_e32 v119, v47, v136
	v_fma_f32 v122, v122, v32, v112
	v_fma_f32 v123, v123, v33, v113
	v_fma_f32 v124, v124, v34, v114
	v_fma_f32 v125, v125, v35, v115
	v_fma_f32 v126, v126, v36, v116
	v_fma_f32 v127, v127, v37, v117
	v_fma_f32 v128, v128, v38, v118
	v_fma_f32 v129, v129, v39, v119
	v_mul_f32_e32 v136, v122, v140
	v_mul_f32_e32 v138, v48, v122
	v_fmac_f32_e32 v136, v123, v141
	v_fmac_f32_e32 v138, v123, v49
	v_fmac_f32_e32 v136, v124, v142
	v_fmac_f32_e32 v138, v124, v50
	v_fmac_f32_e32 v136, v125, v143
	v_fmac_f32_e32 v138, v125, v51
	v_fmac_f32_e32 v136, v126, v144
	v_fmac_f32_e32 v138, v126, v52
	v_fmac_f32_e32 v136, v127, v145
	v_fmac_f32_e32 v138, v127, v53
	v_fmac_f32_e32 v136, v128, v146
	v_fmac_f32_e32 v138, v128, v54
	v_fmac_f32_e32 v136, v129, v147
	v_fmac_f32_e32 v138, v129, v55
	v_mul_f32_e32 v112, v148, v106
	v_mul_f32_e32 v113, v149, v106
	v_add_f32_dpp v136, v136, v136 quad_perm:[1,0,3,2] row_mask:0xf bank_mask:0xf bound_ctrl:1
	v_add_f32_dpp v139, v137, v137 row_half_mirror row_mask:0xf bank_mask:0xf bound_ctrl:1
	v_add_f32_dpp v139, v138, v138 row_half_mirror row_mask:0xf bank_mask:0xa
	v_add_f32_dpp v136, v136, v136 quad_perm:[2,3,0,1] row_mask:0xf bank_mask:0xf bound_ctrl:1
	v_mul_f32_e32 v114, v150, v106
	v_mul_f32_e32 v115, v151, v106
	v_add_f32_dpp v139, v139, v139 quad_perm:[2,3,0,1] row_mask:0xf bank_mask:0xf bound_ctrl:1
	v_add_f32_dpp v136, v136, v136 row_half_mirror row_mask:0xf bank_mask:0xf bound_ctrl:1
	v_mul_f32_e32 v116, v152, v106
	v_mul_f32_e32 v117, v153, v106
	v_add_f32_dpp v139, v139, v139 quad_perm:[1,0,3,2] row_mask:0xf bank_mask:0xf bound_ctrl:1
	v_mul_f32_e32 v118, v154, v106
	v_mul_f32_e32 v119, v155, v106
	ds_write_b32 v135, v139 offset:1792
	ds_read_b128 v[140:143], v133 offset:12800
	ds_read_b128 v[144:147], v133 offset:12816
	ds_read_b128 v[148:151], v133 offset:29184
	ds_read_b128 v[152:155], v133 offset:29200
	ds_read2st64_b32 v[108:109], v134 offset0:178 offset1:179
	ds_read_b128 v[32:35], v133 offset:4352
	ds_read_b128 v[36:39], v133 offset:4368
	ds_read_b128 v[40:43], v133 offset:20736
	ds_read_b128 v[44:47], v133 offset:20752
	ds_read_b128 v[48:51], v133 offset:37120
	ds_read_b128 v[52:55], v133 offset:37136
	s_waitcnt lgkmcnt(11)
	v_fmac_f32_e32 v112, v184, v136
	v_fmac_f32_e32 v113, v185, v136
	v_fmac_f32_e32 v114, v186, v136
	v_fmac_f32_e32 v115, v187, v136
	v_fmac_f32_e32 v116, v188, v136
	v_fmac_f32_e32 v117, v189, v136
	v_fmac_f32_e32 v118, v190, v136
	v_fmac_f32_e32 v119, v191, v136
	v_fma_f32 v122, v122, v176, v112
	v_fma_f32 v123, v123, v177, v113
	v_fma_f32 v124, v124, v178, v114
	v_fma_f32 v125, v125, v179, v115
	v_fma_f32 v126, v126, v180, v116
	v_fma_f32 v127, v127, v181, v117
	v_fma_f32 v128, v128, v182, v118
	v_fma_f32 v129, v129, v183, v119
	v_mul_f32_e32 v136, v122, v158
	v_mul_f32_e32 v137, v192, v122
	v_fmac_f32_e32 v136, v123, v159
	v_fmac_f32_e32 v137, v123, v193
	v_fmac_f32_e32 v136, v124, v160
	v_fmac_f32_e32 v137, v124, v194
	v_fmac_f32_e32 v136, v125, v161
	v_fmac_f32_e32 v137, v125, v195
	v_fmac_f32_e32 v136, v126, v162
	v_fmac_f32_e32 v137, v126, v196
	v_fmac_f32_e32 v136, v127, v163
	v_fmac_f32_e32 v137, v127, v197
	v_fmac_f32_e32 v136, v128, v164
	v_fmac_f32_e32 v137, v128, v198
	v_fmac_f32_e32 v136, v129, v165
	v_fmac_f32_e32 v137, v129, v199
	v_mul_f32_e32 v112, v166, v107
	v_mul_f32_e32 v113, v167, v107
	v_add_f32_dpp v136, v136, v136 quad_perm:[1,0,3,2] row_mask:0xf bank_mask:0xf bound_ctrl:1
	v_mul_f32_e32 v114, v168, v107
	v_mul_f32_e32 v115, v169, v107
	v_add_f32_dpp v136, v136, v136 quad_perm:[2,3,0,1] row_mask:0xf bank_mask:0xf bound_ctrl:1
	v_mul_f32_e32 v116, v170, v107
	v_mul_f32_e32 v117, v171, v107
	v_add_f32_dpp v136, v136, v136 row_half_mirror row_mask:0xf bank_mask:0xf bound_ctrl:1
	v_mul_f32_e32 v118, v172, v107
	v_mul_f32_e32 v119, v173, v107
	ds_read_b128 v[158:161], v133 offset:13056
	ds_read_b128 v[162:165], v133 offset:13072
	ds_read_b128 v[166:169], v133 offset:29440
	ds_read_b128 v[170:173], v133 offset:29456
	ds_read_b128 v[176:179], v133 offset:4608
	ds_read_b128 v[180:183], v133 offset:4624
	ds_read_b128 v[184:187], v133 offset:20992
	ds_read_b128 v[188:191], v133 offset:21008
	ds_read_b128 v[192:195], v133 offset:37376
	ds_read_b128 v[196:199], v133 offset:37392
	s_waitcnt lgkmcnt(10)
; template <int CTRL> __device__ __forceinline__ float dppf(float x) { return __builtin_bit_cast(float, __builtin_amdgcn_mov_dpp(__builtin_bit_cast(int, x), CTRL, 0xf, 0xf, true)); }
; #define LDOPS(s_) do { const float* p_ = bb + (s_) * 64; w4[(s_) % 3] = *(const f32x4*)(p_); a4[(s_) % 3] = *(const f32x4*)(p_ + 2048); b4[(s_) % 3] = *(const f32x4*)(p_ + 4096); k4[(s_) % 3] = *(const f32x4*)(p_ + 6144); \
;               r4[(s_) % 3] = *(const f32x4*)(p_ + 8192); vv[(s_) % 3] = vb[(s_) * 64]; } while (0)
; __device__ __forceinline__ void scan_block(unsigned char* shm, int sid, int half) {
;     ...
;           for (int s = 0; s < TS; ++s) {
;               const f32x4 a_ = a4[s % 3], w_ = w4[s % 3], b_ = b4[s % 3], k_ = k4[s % 3], r_ = r4[s % 3];
;               const float av[4] = {a_.x, a_.y, a_.z, a_.w}, wv[4] = {w_.x, w_.y, w_.z, w_.w}, bv[4] = {b_.x, b_.y, b_.z, b_.w}, kv[4] = {k_.x, k_.y, k_.z, k_.w}, rv[4] = {r_.x, r_.y, r_.z, r_.w};
;               const float v1 = vv[s % 3];
;               if (s + 2 < TS) LDOPS(s + 2);
;               float t = S[0] * av[0]; t = fmaf(S[1], av[1], t); t = fmaf(S[2], av[2], t); t = fmaf(S[3], av[3], t);
;               t += dppf<0xB1>(t); t += dppf<0x4E>(t); t += dppf<0x141>(t); t += dppf<0x140>(t);
; #pragma unroll
;               for (int q = 0; q < 4; ++q) S[q] = fmaf(S[q], wv[q], fmaf(bv[q], t, kv[q] * v1));
;               float u = S[0] * rv[0]; u = fmaf(S[1], rv[1], u); u = fmaf(S[2], rv[2], u); u = fmaf(S[3], rv[3], u);
;               u += dppf<0xB1>(u); u += dppf<0x4E>(u); u += dppf<0x141>(u); u += dppf<0x140>(u);
;               ys[s * 32] = u;
;           }
	v_fmac_f32_e32 v112, v40, v136
	v_fmac_f32_e32 v113, v41, v136
	v_fmac_f32_e32 v114, v42, v136
	v_fmac_f32_e32 v115, v43, v136
	v_fmac_f32_e32 v116, v44, v136
	v_fmac_f32_e32 v117, v45, v136
	v_fmac_f32_e32 v118, v46, v136
	v_fmac_f32_e32 v119, v47, v136
	v_fma_f32 v122, v122, v32, v112
	v_fma_f32 v123, v123, v33, v113
	v_fma_f32 v124, v124, v34, v114
	v_fma_f32 v125, v125, v35, v115
	v_fma_f32 v126, v126, v36, v116
	v_fma_f32 v127, v127, v37, v117
	v_fma_f32 v128, v128, v38, v118
	v_fma_f32 v129, v129, v39, v119
	v_mul_f32_e32 v136, v122, v140
	v_mul_f32_e32 v138, v48, v122
	v_fmac_f32_e32 v136, v123, v141
	v_fmac_f32_e32 v138, v123, v49
	v_fmac_f32_e32 v136, v124, v142
	v_fmac_f32_e32 v138, v124, v50
	v_fmac_f32_e32 v136, v125, v143
	v_fmac_f32_e32 v138, v125, v51
	v_fmac_f32_e32 v136, v126, v144
	v_fmac_f32_e32 v138, v126, v52
	v_fmac_f32_e32 v136, v127, v145
	v_fmac_f32_e32 v138, v127, v53
	v_fmac_f32_e32 v136, v128, v146
	v_fmac_f32_e32 v138, v128, v54
	v_fmac_f32_e32 v136, v129, v147
	v_fmac_f32_e32 v138, v129, v55
	v_mul_f32_e32 v112, v148, v108
	v_mul_f32_e32 v113, v149, v108
	v_add_f32_dpp v136, v136, v136 quad_perm:[1,0,3,2] row_mask:0xf bank_mask:0xf bound_ctrl:1
	v_add_f32_dpp v139, v137, v137 row_half_mirror row_mask:0xf bank_mask:0xf bound_ctrl:1
	v_add_f32_dpp v139, v138, v138 row_half_mirror row_mask:0xf bank_mask:0xa
	v_add_f32_dpp v136, v136, v136 quad_perm:[2,3,0,1] row_mask:0xf bank_mask:0xf bound_ctrl:1
	v_mul_f32_e32 v114, v150, v108
	v_mul_f32_e32 v115, v151, v108
	v_add_f32_dpp v139, v139, v139 quad_perm:[2,3,0,1] row_mask:0xf bank_mask:0xf bound_ctrl:1
	v_add_f32_dpp v136, v136, v136 row_half_mirror row_mask:0xf bank_mask:0xf bound_ctrl:1
	v_mul_f32_e32 v116, v152, v108
	v_mul_f32_e32 v117, v153, v108
	v_add_f32_dpp v139, v139, v139 quad_perm:[1,0,3,2] row_mask:0xf bank_mask:0xf bound_ctrl:1
	v_mul_f32_e32 v118, v154, v108
	v_mul_f32_e32 v119, v155, v108
	ds_write_b32 v135, v139 offset:2048
	ds_read_b128 v[140:143], v133 offset:13312
	ds_read_b128 v[144:147], v133 offset:13328
	ds_read_b128 v[148:151], v133 offset:29696
	ds_read_b128 v[152:155], v133 offset:29712
	ds_read2st64_b32 v[106:107], v134 offset0:180 offset1:181
	ds_read_b128 v[32:35], v133 offset:4864
	ds_read_b128 v[36:39], v133 offset:4880
	ds_read_b128 v[40:43], v133 offset:21248
	ds_read_b128 v[44:47], v133 offset:21264
	ds_read_b128 v[48:51], v133 offset:37632
	ds_read_b128 v[52:55], v133 offset:37648
	s_waitcnt lgkmcnt(11)
	v_fmac_f32_e32 v112, v184, v136
	v_fmac_f32_e32 v113, v185, v136
	v_fmac_f32_e32 v114, v186, v136
	v_fmac_f32_e32 v115, v187, v136
	v_fmac_f32_e32 v116, v188, v136
	v_fmac_f32_e32 v117, v189, v136
	v_fmac_f32_e32 v118, v190, v136
	v_fmac_f32_e32 v119, v191, v136
	v_fma_f32 v122, v122, v176, v112
	v_fma_f32 v123, v123, v177, v113
	v_fma_f32 v124, v124, v178, v114
	v_fma_f32 v125, v125, v179, v115
	v_fma_f32 v126, v126, v180, v116
	v_fma_f32 v127, v127, v181, v117
	v_fma_f32 v128, v128, v182, v118
	v_fma_f32 v129, v129, v183, v119
	v_mul_f32_e32 v136, v122, v158
	v_mul_f32_e32 v137, v192, v122
	v_fmac_f32_e32 v136, v123, v159
	v_fmac_f32_e32 v137, v123, v193
	v_fmac_f32_e32 v136, v124, v160
	v_fmac_f32_e32 v137, v124, v194
	v_fmac_f32_e32 v136, v125, v161
	v_fmac_f32_e32 v137, v125, v195
	v_fmac_f32_e32 v136, v126, v162
	v_fmac_f32_e32 v137, v126, v196
	v_fmac_f32_e32 v136, v127, v163
	v_fmac_f32_e32 v137, v127, v197
	v_fmac_f32_e32 v136, v128, v164
	v_fmac_f32_e32 v137, v128, v198
	v_fmac_f32_e32 v136, v129, v165
	v_fmac_f32_e32 v137, v129, v199
	v_mul_f32_e32 v112, v166, v109
	v_mul_f32_e32 v113, v167, v109
	v_add_f32_dpp v136, v136, v136 quad_perm:[1,0,3,2] row_mask:0xf bank_mask:0xf bound_ctrl:1
	v_mul_f32_e32 v114, v168, v109
	v_mul_f32_e32 v115, v169, v109
	v_add_f32_dpp v136, v136, v136 quad_perm:[2,3,0,1] row_mask:0xf bank_mask:0xf bound_ctrl:1
	v_mul_f32_e32 v116, v170, v109
	v_mul_f32_e32 v117, v171, v109
	v_add_f32_dpp v136, v136, v136 row_half_mirror row_mask:0xf bank_mask:0xf bound_ctrl:1
	v_mul_f32_e32 v118, v172, v109
	v_mul_f32_e32 v119, v173, v109
	ds_read_b128 v[158:161], v133 offset:13568
	ds_read_b128 v[162:165], v133 offset:13584
	ds_read_b128 v[166:169], v133 offset:29952
	ds_read_b128 v[170:173], v133 offset:29968
	ds_read_b128 v[176:179], v133 offset:5120
	ds_read_b128 v[180:183], v133 offset:5136
	ds_read_b128 v[184:187], v133 offset:21504
	ds_read_b128 v[188:191], v133 offset:21520
	ds_read_b128 v[192:195], v133 offset:37888
	ds_read_b128 v[196:199], v133 offset:37904
	s_waitcnt lgkmcnt(10)
; template <int CTRL> __device__ __forceinline__ float dppf(float x) { return __builtin_bit_cast(float, __builtin_amdgcn_mov_dpp(__builtin_bit_cast(int, x), CTRL, 0xf, 0xf, true)); }
; #define LDOPS(s_) do { const float* p_ = bb + (s_) * 64; w4[(s_) % 3] = *(const f32x4*)(p_); a4[(s_) % 3] = *(const f32x4*)(p_ + 2048); b4[(s_) % 3] = *(const f32x4*)(p_ + 4096); k4[(s_) % 3] = *(const f32x4*)(p_ + 6144); \
;               r4[(s_) % 3] = *(const f32x4*)(p_ + 8192); vv[(s_) % 3] = vb[(s_) * 64]; } while (0)
; __device__ __forceinline__ void scan_block(unsigned char* shm, int sid, int half) {
;     ...
;           for (int s = 0; s < TS; ++s) {
;               const f32x4 a_ = a4[s % 3], w_ = w4[s % 3], b_ = b4[s % 3], k_ = k4[s % 3], r_ = r4[s % 3];
;               const float av[4] = {a_.x, a_.y, a_.z, a_.w}, wv[4] = {w_.x, w_.y, w_.z, w_.w}, bv[4] = {b_.x, b_.y, b_.z, b_.w}, kv[4] = {k_.x, k_.y, k_.z, k_.w}, rv[4] = {r_.x, r_.y, r_.z, r_.w};
;               const float v1 = vv[s % 3];
;               if (s + 2 < TS) LDOPS(s + 2);
;               float t = S[0] * av[0]; t = fmaf(S[1], av[1], t); t = fmaf(S[2], av[2], t); t = fmaf(S[3], av[3], t);
;               t += dppf<0xB1>(t); t += dppf<0x4E>(t); t += dppf<0x141>(t); t += dppf<0x140>(t);
; #pragma unroll
;               for (int q = 0; q < 4; ++q) S[q] = fmaf(S[q], wv[q], fmaf(bv[q], t, kv[q] * v1));
;               float u = S[0] * rv[0]; u = fmaf(S[1], rv[1], u); u = fmaf(S[2], rv[2], u); u = fmaf(S[3], rv[3], u);
;               u += dppf<0xB1>(u); u += dppf<0x4E>(u); u += dppf<0x141>(u); u += dppf<0x140>(u);
;               ys[s * 32] = u;
;           }
	v_fmac_f32_e32 v112, v40, v136
	v_fmac_f32_e32 v113, v41, v136
	v_fmac_f32_e32 v114, v42, v136
	v_fmac_f32_e32 v115, v43, v136
	v_fmac_f32_e32 v116, v44, v136
	v_fmac_f32_e32 v117, v45, v136
	v_fmac_f32_e32 v118, v46, v136
	v_fmac_f32_e32 v119, v47, v136
	v_fma_f32 v122, v122, v32, v112
	v_fma_f32 v123, v123, v33, v113
	v_fma_f32 v124, v124, v34, v114
	v_fma_f32 v125, v125, v35, v115
	v_fma_f32 v126, v126, v36, v116
	v_fma_f32 v127, v127, v37, v117
	v_fma_f32 v128, v128, v38, v118
	v_fma_f32 v129, v129, v39, v119
	v_mul_f32_e32 v136, v122, v140
	v_mul_f32_e32 v138, v48, v122
	v_fmac_f32_e32 v136, v123, v141
	v_fmac_f32_e32 v138, v123, v49
	v_fmac_f32_e32 v136, v124, v142
	v_fmac_f32_e32 v138, v124, v50
	v_fmac_f32_e32 v136, v125, v143
	v_fmac_f32_e32 v138, v125, v51
	v_fmac_f32_e32 v136, v126, v144
	v_fmac_f32_e32 v138, v126, v52
	v_fmac_f32_e32 v136, v127, v145
	v_fmac_f32_e32 v138, v127, v53
	v_fmac_f32_e32 v136, v128, v146
	v_fmac_f32_e32 v138, v128, v54
	v_fmac_f32_e32 v136, v129, v147
	v_fmac_f32_e32 v138, v129, v55
	v_mul_f32_e32 v112, v148, v106
	v_mul_f32_e32 v113, v149, v106
	v_add_f32_dpp v136, v136, v136 quad_perm:[1,0,3,2] row_mask:0xf bank_mask:0xf bound_ctrl:1
	v_add_f32_dpp v139, v137, v137 row_half_mirror row_mask:0xf bank_mask:0xf bound_ctrl:1
	v_add_f32_dpp v139, v138, v138 row_half_mirror row_mask:0xf bank_mask:0xa
	v_add_f32_dpp v136, v136, v136 quad_perm:[2,3,0,1] row_mask:0xf bank_mask:0xf bound_ctrl:1
	v_mul_f32_e32 v114, v150, v106
	v_mul_f32_e32 v115, v151, v106
	v_add_f32_dpp v139, v139, v139 quad_perm:[2,3,0,1] row_mask:0xf bank_mask:0xf bound_ctrl:1
	v_add_f32_dpp v136, v136, v136 row_half_mirror row_mask:0xf bank_mask:0xf bound_ctrl:1
	v_mul_f32_e32 v116, v152, v106
	v_mul_f32_e32 v117, v153, v106
	v_add_f32_dpp v139, v139, v139 quad_perm:[1,0,3,2] row_mask:0xf bank_mask:0xf bound_ctrl:1
	v_mul_f32_e32 v118, v154, v106
	v_mul_f32_e32 v119, v155, v106
	ds_write_b32 v135, v139 offset:2304
	ds_read_b128 v[140:143], v133 offset:13824
	ds_read_b128 v[144:147], v133 offset:13840
	ds_read_b128 v[148:151], v133 offset:30208
	ds_read_b128 v[152:155], v133 offset:30224
	ds_read2st64_b32 v[108:109], v134 offset0:182 offset1:183
	ds_read_b128 v[32:35], v133 offset:5376
	ds_read_b128 v[36:39], v133 offset:5392
	ds_read_b128 v[40:43], v133 offset:21760
	ds_read_b128 v[44:47], v133 offset:21776
	ds_read_b128 v[48:51], v133 offset:38144
	ds_read_b128 v[52:55], v133 offset:38160
	s_waitcnt lgkmcnt(11)
	v_fmac_f32_e32 v112, v184, v136
	v_fmac_f32_e32 v113, v185, v136
	v_fmac_f32_e32 v114, v186, v136
	v_fmac_f32_e32 v115, v187, v136
	v_fmac_f32_e32 v116, v188, v136
	v_fmac_f32_e32 v117, v189, v136
	v_fmac_f32_e32 v118, v190, v136
	v_fmac_f32_e32 v119, v191, v136
	v_fma_f32 v122, v122, v176, v112
	v_fma_f32 v123, v123, v177, v113
	v_fma_f32 v124, v124, v178, v114
	v_fma_f32 v125, v125, v179, v115
	v_fma_f32 v126, v126, v180, v116
	v_fma_f32 v127, v127, v181, v117
	v_fma_f32 v128, v128, v182, v118
	v_fma_f32 v129, v129, v183, v119
	v_mul_f32_e32 v136, v122, v158
	v_mul_f32_e32 v137, v192, v122
	v_fmac_f32_e32 v136, v123, v159
	v_fmac_f32_e32 v137, v123, v193
	v_fmac_f32_e32 v136, v124, v160
	v_fmac_f32_e32 v137, v124, v194
	v_fmac_f32_e32 v136, v125, v161
	v_fmac_f32_e32 v137, v125, v195
	v_fmac_f32_e32 v136, v126, v162
	v_fmac_f32_e32 v137, v126, v196
	v_fmac_f32_e32 v136, v127, v163
	v_fmac_f32_e32 v137, v127, v197
	v_fmac_f32_e32 v136, v128, v164
	v_fmac_f32_e32 v137, v128, v198
	v_fmac_f32_e32 v136, v129, v165
	v_fmac_f32_e32 v137, v129, v199
	v_mul_f32_e32 v112, v166, v107
	v_mul_f32_e32 v113, v167, v107
	v_add_f32_dpp v136, v136, v136 quad_perm:[1,0,3,2] row_mask:0xf bank_mask:0xf bound_ctrl:1
	v_mul_f32_e32 v114, v168, v107
	v_mul_f32_e32 v115, v169, v107
	v_add_f32_dpp v136, v136, v136 quad_perm:[2,3,0,1] row_mask:0xf bank_mask:0xf bound_ctrl:1
	v_mul_f32_e32 v116, v170, v107
	v_mul_f32_e32 v117, v171, v107
	v_add_f32_dpp v136, v136, v136 row_half_mirror row_mask:0xf bank_mask:0xf bound_ctrl:1
	v_mul_f32_e32 v118, v172, v107
	v_mul_f32_e32 v119, v173, v107
	ds_read_b128 v[158:161], v133 offset:14080
	ds_read_b128 v[162:165], v133 offset:14096
	ds_read_b128 v[166:169], v133 offset:30464
	ds_read_b128 v[170:173], v133 offset:30480
	ds_read_b128 v[176:179], v133 offset:5632
	ds_read_b128 v[180:183], v133 offset:5648
	ds_read_b128 v[184:187], v133 offset:22016
	ds_read_b128 v[188:191], v133 offset:22032
	ds_read_b128 v[192:195], v133 offset:38400
	ds_read_b128 v[196:199], v133 offset:38416
	s_waitcnt lgkmcnt(10)
; template <int CTRL> __device__ __forceinline__ float dppf(float x) { return __builtin_bit_cast(float, __builtin_amdgcn_mov_dpp(__builtin_bit_cast(int, x), CTRL, 0xf, 0xf, true)); }
; #define LDOPS(s_) do { const float* p_ = bb + (s_) * 64; w4[(s_) % 3] = *(const f32x4*)(p_); a4[(s_) % 3] = *(const f32x4*)(p_ + 2048); b4[(s_) % 3] = *(const f32x4*)(p_ + 4096); k4[(s_) % 3] = *(const f32x4*)(p_ + 6144); \
;               r4[(s_) % 3] = *(const f32x4*)(p_ + 8192); vv[(s_) % 3] = vb[(s_) * 64]; } while (0)
; __device__ __forceinline__ void scan_block(unsigned char* shm, int sid, int half) {
;     ...
;           for (int s = 0; s < TS; ++s) {
;               const f32x4 a_ = a4[s % 3], w_ = w4[s % 3], b_ = b4[s % 3], k_ = k4[s % 3], r_ = r4[s % 3];
;               const float av[4] = {a_.x, a_.y, a_.z, a_.w}, wv[4] = {w_.x, w_.y, w_.z, w_.w}, bv[4] = {b_.x, b_.y, b_.z, b_.w}, kv[4] = {k_.x, k_.y, k_.z, k_.w}, rv[4] = {r_.x, r_.y, r_.z, r_.w};
;               const float v1 = vv[s % 3];
;               if (s + 2 < TS) LDOPS(s + 2);
;               float t = S[0] * av[0]; t = fmaf(S[1], av[1], t); t = fmaf(S[2], av[2], t); t = fmaf(S[3], av[3], t);
;               t += dppf<0xB1>(t); t += dppf<0x4E>(t); t += dppf<0x141>(t); t += dppf<0x140>(t);
; #pragma unroll
;               for (int q = 0; q < 4; ++q) S[q] = fmaf(S[q], wv[q], fmaf(bv[q], t, kv[q] * v1));
;               float u = S[0] * rv[0]; u = fmaf(S[1], rv[1], u); u = fmaf(S[2], rv[2], u); u = fmaf(S[3], rv[3], u);
;               u += dppf<0xB1>(u); u += dppf<0x4E>(u); u += dppf<0x141>(u); u += dppf<0x140>(u);
;               ys[s * 32] = u;
;           }
	v_fmac_f32_e32 v112, v40, v136
	v_fmac_f32_e32 v113, v41, v136
	v_fmac_f32_e32 v114, v42, v136
	v_fmac_f32_e32 v115, v43, v136
	v_fmac_f32_e32 v116, v44, v136
	v_fmac_f32_e32 v117, v45, v136
	v_fmac_f32_e32 v118, v46, v136
	v_fmac_f32_e32 v119, v47, v136
	v_fma_f32 v122, v122, v32, v112
	v_fma_f32 v123, v123, v33, v113
	v_fma_f32 v124, v124, v34, v114
	v_fma_f32 v125, v125, v35, v115
	v_fma_f32 v126, v126, v36, v116
	v_fma_f32 v127, v127, v37, v117
	v_fma_f32 v128, v128, v38, v118
	v_fma_f32 v129, v129, v39, v119
	v_mul_f32_e32 v136, v122, v140
	v_mul_f32_e32 v138, v48, v122
	v_fmac_f32_e32 v136, v123, v141
	v_fmac_f32_e32 v138, v123, v49
	v_fmac_f32_e32 v136, v124, v142
	v_fmac_f32_e32 v138, v124, v50
	v_fmac_f32_e32 v136, v125, v143
	v_fmac_f32_e32 v138, v125, v51
	v_fmac_f32_e32 v136, v126, v144
	v_fmac_f32_e32 v138, v126, v52
	v_fmac_f32_e32 v136, v127, v145
	v_fmac_f32_e32 v138, v127, v53
	v_fmac_f32_e32 v136, v128, v146
	v_fmac_f32_e32 v138, v128, v54
	v_fmac_f32_e32 v136, v129, v147
	v_fmac_f32_e32 v138, v129, v55
	v_mul_f32_e32 v112, v148, v108
	v_mul_f32_e32 v113, v149, v108
	v_add_f32_dpp v136, v136, v136 quad_perm:[1,0,3,2] row_mask:0xf bank_mask:0xf bound_ctrl:1
	v_add_f32_dpp v139, v137, v137 row_half_mirror row_mask:0xf bank_mask:0xf bound_ctrl:1
	v_add_f32_dpp v139, v138, v138 row_half_mirror row_mask:0xf bank_mask:0xa
	v_add_f32_dpp v136, v136, v136 quad_perm:[2,3,0,1] row_mask:0xf bank_mask:0xf bound_ctrl:1
	v_mul_f32_e32 v114, v150, v108
	v_mul_f32_e32 v115, v151, v108
	v_add_f32_dpp v139, v139, v139 quad_perm:[2,3,0,1] row_mask:0xf bank_mask:0xf bound_ctrl:1
	v_add_f32_dpp v136, v136, v136 row_half_mirror row_mask:0xf bank_mask:0xf bound_ctrl:1
	v_mul_f32_e32 v116, v152, v108
	v_mul_f32_e32 v117, v153, v108
	v_add_f32_dpp v139, v139, v139 quad_perm:[1,0,3,2] row_mask:0xf bank_mask:0xf bound_ctrl:1
	v_mul_f32_e32 v118, v154, v108
	v_mul_f32_e32 v119, v155, v108
	ds_write_b32 v135, v139 offset:2560
	ds_read_b128 v[140:143], v133 offset:14336
	ds_read_b128 v[144:147], v133 offset:14352
	ds_read_b128 v[148:151], v133 offset:30720
	ds_read_b128 v[152:155], v133 offset:30736
	ds_read2st64_b32 v[106:107], v134 offset0:184 offset1:185
	ds_read_b128 v[32:35], v133 offset:5888
	ds_read_b128 v[36:39], v133 offset:5904
	ds_read_b128 v[40:43], v133 offset:22272
	ds_read_b128 v[44:47], v133 offset:22288
	ds_read_b128 v[48:51], v133 offset:38656
	ds_read_b128 v[52:55], v133 offset:38672
	s_waitcnt lgkmcnt(11)
	v_fmac_f32_e32 v112, v184, v136
	v_fmac_f32_e32 v113, v185, v136
	v_fmac_f32_e32 v114, v186, v136
	v_fmac_f32_e32 v115, v187, v136
	v_fmac_f32_e32 v116, v188, v136
	v_fmac_f32_e32 v117, v189, v136
	v_fmac_f32_e32 v118, v190, v136
	v_fmac_f32_e32 v119, v191, v136
	v_fma_f32 v122, v122, v176, v112
	v_fma_f32 v123, v123, v177, v113
	v_fma_f32 v124, v124, v178, v114
	v_fma_f32 v125, v125, v179, v115
	v_fma_f32 v126, v126, v180, v116
	v_fma_f32 v127, v127, v181, v117
	v_fma_f32 v128, v128, v182, v118
	v_fma_f32 v129, v129, v183, v119
	v_mul_f32_e32 v136, v122, v158
	v_mul_f32_e32 v137, v192, v122
	v_fmac_f32_e32 v136, v123, v159
	v_fmac_f32_e32 v137, v123, v193
	v_fmac_f32_e32 v136, v124, v160
	v_fmac_f32_e32 v137, v124, v194
	v_fmac_f32_e32 v136, v125, v161
	v_fmac_f32_e32 v137, v125, v195
	v_fmac_f32_e32 v136, v126, v162
	v_fmac_f32_e32 v137, v126, v196
	v_fmac_f32_e32 v136, v127, v163
	v_fmac_f32_e32 v137, v127, v197
	v_fmac_f32_e32 v136, v128, v164
	v_fmac_f32_e32 v137, v128, v198
	v_fmac_f32_e32 v136, v129, v165
	v_fmac_f32_e32 v137, v129, v199
	v_mul_f32_e32 v112, v166, v109
	v_mul_f32_e32 v113, v167, v109
	v_add_f32_dpp v136, v136, v136 quad_perm:[1,0,3,2] row_mask:0xf bank_mask:0xf bound_ctrl:1
	v_mul_f32_e32 v114, v168, v109
	v_mul_f32_e32 v115, v169, v109
	v_add_f32_dpp v136, v136, v136 quad_perm:[2,3,0,1] row_mask:0xf bank_mask:0xf bound_ctrl:1
	v_mul_f32_e32 v116, v170, v109
	v_mul_f32_e32 v117, v171, v109
	v_add_f32_dpp v136, v136, v136 row_half_mirror row_mask:0xf bank_mask:0xf bound_ctrl:1
	v_mul_f32_e32 v118, v172, v109
	v_mul_f32_e32 v119, v173, v109
	ds_read_b128 v[158:161], v133 offset:14592
	ds_read_b128 v[162:165], v133 offset:14608
	ds_read_b128 v[166:169], v133 offset:30976
	ds_read_b128 v[170:173], v133 offset:30992
	ds_read_b128 v[176:179], v133 offset:6144
	ds_read_b128 v[180:183], v133 offset:6160
	ds_read_b128 v[184:187], v133 offset:22528
	ds_read_b128 v[188:191], v133 offset:22544
	ds_read_b128 v[192:195], v133 offset:38912
	ds_read_b128 v[196:199], v133 offset:38928
	s_waitcnt lgkmcnt(10)
; template <int CTRL> __device__ __forceinline__ float dppf(float x) { return __builtin_bit_cast(float, __builtin_amdgcn_mov_dpp(__builtin_bit_cast(int, x), CTRL, 0xf, 0xf, true)); }
; #define LDOPS(s_) do { const float* p_ = bb + (s_) * 64; w4[(s_) % 3] = *(const f32x4*)(p_); a4[(s_) % 3] = *(const f32x4*)(p_ + 2048); b4[(s_) % 3] = *(const f32x4*)(p_ + 4096); k4[(s_) % 3] = *(const f32x4*)(p_ + 6144); \
;               r4[(s_) % 3] = *(const f32x4*)(p_ + 8192); vv[(s_) % 3] = vb[(s_) * 64]; } while (0)
; __device__ __forceinline__ void scan_block(unsigned char* shm, int sid, int half) {
;     ...
;           for (int s = 0; s < TS; ++s) {
;               const f32x4 a_ = a4[s % 3], w_ = w4[s % 3], b_ = b4[s % 3], k_ = k4[s % 3], r_ = r4[s % 3];
;               const float av[4] = {a_.x, a_.y, a_.z, a_.w}, wv[4] = {w_.x, w_.y, w_.z, w_.w}, bv[4] = {b_.x, b_.y, b_.z, b_.w}, kv[4] = {k_.x, k_.y, k_.z, k_.w}, rv[4] = {r_.x, r_.y, r_.z, r_.w};
;               const float v1 = vv[s % 3];
;               if (s + 2 < TS) LDOPS(s + 2);
;               float t = S[0] * av[0]; t = fmaf(S[1], av[1], t); t = fmaf(S[2], av[2], t); t = fmaf(S[3], av[3], t);
;               t += dppf<0xB1>(t); t += dppf<0x4E>(t); t += dppf<0x141>(t); t += dppf<0x140>(t);
; #pragma unroll
;               for (int q = 0; q < 4; ++q) S[q] = fmaf(S[q], wv[q], fmaf(bv[q], t, kv[q] * v1));
;               float u = S[0] * rv[0]; u = fmaf(S[1], rv[1], u); u = fmaf(S[2], rv[2], u); u = fmaf(S[3], rv[3], u);
;               u += dppf<0xB1>(u); u += dppf<0x4E>(u); u += dppf<0x141>(u); u += dppf<0x140>(u);
;               ys[s * 32] = u;
;           }
	v_fmac_f32_e32 v112, v40, v136
	v_fmac_f32_e32 v113, v41, v136
	v_fmac_f32_e32 v114, v42, v136
	v_fmac_f32_e32 v115, v43, v136
	v_fmac_f32_e32 v116, v44, v136
	v_fmac_f32_e32 v117, v45, v136
	v_fmac_f32_e32 v118, v46, v136
	v_fmac_f32_e32 v119, v47, v136
	v_fma_f32 v122, v122, v32, v112
	v_fma_f32 v123, v123, v33, v113
	v_fma_f32 v124, v124, v34, v114
	v_fma_f32 v125, v125, v35, v115
	v_fma_f32 v126, v126, v36, v116
	v_fma_f32 v127, v127, v37, v117
	v_fma_f32 v128, v128, v38, v118
	v_fma_f32 v129, v129, v39, v119
	v_mul_f32_e32 v136, v122, v140
	v_mul_f32_e32 v138, v48, v122
	v_fmac_f32_e32 v136, v123, v141
	v_fmac_f32_e32 v138, v123, v49
	v_fmac_f32_e32 v136, v124, v142
	v_fmac_f32_e32 v138, v124, v50
	v_fmac_f32_e32 v136, v125, v143
	v_fmac_f32_e32 v138, v125, v51
	v_fmac_f32_e32 v136, v126, v144
	v_fmac_f32_e32 v138, v126, v52
	v_fmac_f32_e32 v136, v127, v145
	v_fmac_f32_e32 v138, v127, v53
	v_fmac_f32_e32 v136, v128, v146
	v_fmac_f32_e32 v138, v128, v54
	v_fmac_f32_e32 v136, v129, v147
	v_fmac_f32_e32 v138, v129, v55
	v_mul_f32_e32 v112, v148, v106
	v_mul_f32_e32 v113, v149, v106
	v_add_f32_dpp v136, v136, v136 quad_perm:[1,0,3,2] row_mask:0xf bank_mask:0xf bound_ctrl:1
	v_add_f32_dpp v139, v137, v137 row_half_mirror row_mask:0xf bank_mask:0xf bound_ctrl:1
	v_add_f32_dpp v139, v138, v138 row_half_mirror row_mask:0xf bank_mask:0xa
	v_add_f32_dpp v136, v136, v136 quad_perm:[2,3,0,1] row_mask:0xf bank_mask:0xf bound_ctrl:1
	v_mul_f32_e32 v114, v150, v106
	v_mul_f32_e32 v115, v151, v106
	v_add_f32_dpp v139, v139, v139 quad_perm:[2,3,0,1] row_mask:0xf bank_mask:0xf bound_ctrl:1
	v_add_f32_dpp v136, v136, v136 row_half_mirror row_mask:0xf bank_mask:0xf bound_ctrl:1
	v_mul_f32_e32 v116, v152, v106
	v_mul_f32_e32 v117, v153, v106
	v_add_f32_dpp v139, v139, v139 quad_perm:[1,0,3,2] row_mask:0xf bank_mask:0xf bound_ctrl:1
	v_mul_f32_e32 v118, v154, v106
	v_mul_f32_e32 v119, v155, v106
	ds_write_b32 v135, v139 offset:2816
	ds_read_b128 v[140:143], v133 offset:14848
	ds_read_b128 v[144:147], v133 offset:14864
	ds_read_b128 v[148:151], v133 offset:31232
	ds_read_b128 v[152:155], v133 offset:31248
	ds_read2st64_b32 v[108:109], v134 offset0:186 offset1:187
	ds_read_b128 v[32:35], v133 offset:6400
	ds_read_b128 v[36:39], v133 offset:6416
	ds_read_b128 v[40:43], v133 offset:22784
	ds_read_b128 v[44:47], v133 offset:22800
	ds_read_b128 v[48:51], v133 offset:39168
	ds_read_b128 v[52:55], v133 offset:39184
	s_waitcnt lgkmcnt(11)
	v_fmac_f32_e32 v112, v184, v136
	v_fmac_f32_e32 v113, v185, v136
	v_fmac_f32_e32 v114, v186, v136
	v_fmac_f32_e32 v115, v187, v136
	v_fmac_f32_e32 v116, v188, v136
	v_fmac_f32_e32 v117, v189, v136
	v_fmac_f32_e32 v118, v190, v136
	v_fmac_f32_e32 v119, v191, v136
	v_fma_f32 v122, v122, v176, v112
	v_fma_f32 v123, v123, v177, v113
	v_fma_f32 v124, v124, v178, v114
	v_fma_f32 v125, v125, v179, v115
	v_fma_f32 v126, v126, v180, v116
	v_fma_f32 v127, v127, v181, v117
	v_fma_f32 v128, v128, v182, v118
	v_fma_f32 v129, v129, v183, v119
	v_mul_f32_e32 v136, v122, v158
	v_mul_f32_e32 v137, v192, v122
	v_fmac_f32_e32 v136, v123, v159
	v_fmac_f32_e32 v137, v123, v193
	v_fmac_f32_e32 v136, v124, v160
	v_fmac_f32_e32 v137, v124, v194
	v_fmac_f32_e32 v136, v125, v161
	v_fmac_f32_e32 v137, v125, v195
	v_fmac_f32_e32 v136, v126, v162
	v_fmac_f32_e32 v137, v126, v196
	v_fmac_f32_e32 v136, v127, v163
	v_fmac_f32_e32 v137, v127, v197
	v_fmac_f32_e32 v136, v128, v164
	v_fmac_f32_e32 v137, v128, v198
	v_fmac_f32_e32 v136, v129, v165
	v_fmac_f32_e32 v137, v129, v199
	v_mul_f32_e32 v112, v166, v107
	v_mul_f32_e32 v113, v167, v107
	v_add_f32_dpp v136, v136, v136 quad_perm:[1,0,3,2] row_mask:0xf bank_mask:0xf bound_ctrl:1
	v_mul_f32_e32 v114, v168, v107
	v_mul_f32_e32 v115, v169, v107
	v_add_f32_dpp v136, v136, v136 quad_perm:[2,3,0,1] row_mask:0xf bank_mask:0xf bound_ctrl:1
	v_mul_f32_e32 v116, v170, v107
	v_mul_f32_e32 v117, v171, v107
	v_add_f32_dpp v136, v136, v136 row_half_mirror row_mask:0xf bank_mask:0xf bound_ctrl:1
	v_mul_f32_e32 v118, v172, v107
	v_mul_f32_e32 v119, v173, v107
	ds_read_b128 v[158:161], v133 offset:15104
	ds_read_b128 v[162:165], v133 offset:15120
	ds_read_b128 v[166:169], v133 offset:31488
	ds_read_b128 v[170:173], v133 offset:31504
	ds_read_b128 v[176:179], v133 offset:6656
	ds_read_b128 v[180:183], v133 offset:6672
	ds_read_b128 v[184:187], v133 offset:23040
	ds_read_b128 v[188:191], v133 offset:23056
	ds_read_b128 v[192:195], v133 offset:39424
	ds_read_b128 v[196:199], v133 offset:39440
	s_waitcnt lgkmcnt(10)
; template <int CTRL> __device__ __forceinline__ float dppf(float x) { return __builtin_bit_cast(float, __builtin_amdgcn_mov_dpp(__builtin_bit_cast(int, x), CTRL, 0xf, 0xf, true)); }
; #define LDOPS(s_) do { const float* p_ = bb + (s_) * 64; w4[(s_) % 3] = *(const f32x4*)(p_); a4[(s_) % 3] = *(const f32x4*)(p_ + 2048); b4[(s_) % 3] = *(const f32x4*)(p_ + 4096); k4[(s_) % 3] = *(const f32x4*)(p_ + 6144); \
;               r4[(s_) % 3] = *(const f32x4*)(p_ + 8192); vv[(s_) % 3] = vb[(s_) * 64]; } while (0)
; __device__ __forceinline__ void scan_block(unsigned char* shm, int sid, int half) {
;     ...
;           for (int s = 0; s < TS; ++s) {
;               const f32x4 a_ = a4[s % 3], w_ = w4[s % 3], b_ = b4[s % 3], k_ = k4[s % 3], r_ = r4[s % 3];
;               const float av[4] = {a_.x, a_.y, a_.z, a_.w}, wv[4] = {w_.x, w_.y, w_.z, w_.w}, bv[4] = {b_.x, b_.y, b_.z, b_.w}, kv[4] = {k_.x, k_.y, k_.z, k_.w}, rv[4] = {r_.x, r_.y, r_.z, r_.w};
;               const float v1 = vv[s % 3];
;               if (s + 2 < TS) LDOPS(s + 2);
;               float t = S[0] * av[0]; t = fmaf(S[1], av[1], t); t = fmaf(S[2], av[2], t); t = fmaf(S[3], av[3], t);
;               t += dppf<0xB1>(t); t += dppf<0x4E>(t); t += dppf<0x141>(t); t += dppf<0x140>(t);
; #pragma unroll
;               for (int q = 0; q < 4; ++q) S[q] = fmaf(S[q], wv[q], fmaf(bv[q], t, kv[q] * v1));
;               float u = S[0] * rv[0]; u = fmaf(S[1], rv[1], u); u = fmaf(S[2], rv[2], u); u = fmaf(S[3], rv[3], u);
;               u += dppf<0xB1>(u); u += dppf<0x4E>(u); u += dppf<0x141>(u); u += dppf<0x140>(u);
;               ys[s * 32] = u;
;           }
	v_fmac_f32_e32 v112, v40, v136
	v_fmac_f32_e32 v113, v41, v136
	v_fmac_f32_e32 v114, v42, v136
	v_fmac_f32_e32 v115, v43, v136
	v_fmac_f32_e32 v116, v44, v136
	v_fmac_f32_e32 v117, v45, v136
	v_fmac_f32_e32 v118, v46, v136
	v_fmac_f32_e32 v119, v47, v136
	v_fma_f32 v122, v122, v32, v112
	v_fma_f32 v123, v123, v33, v113
	v_fma_f32 v124, v124, v34, v114
	v_fma_f32 v125, v125, v35, v115
	v_fma_f32 v126, v126, v36, v116
	v_fma_f32 v127, v127, v37, v117
	v_fma_f32 v128, v128, v38, v118
	v_fma_f32 v129, v129, v39, v119
	v_mul_f32_e32 v136, v122, v140
	v_mul_f32_e32 v138, v48, v122
	v_fmac_f32_e32 v136, v123, v141
	v_fmac_f32_e32 v138, v123, v49
	v_fmac_f32_e32 v136, v124, v142
	v_fmac_f32_e32 v138, v124, v50
	v_fmac_f32_e32 v136, v125, v143
	v_fmac_f32_e32 v138, v125, v51
	v_fmac_f32_e32 v136, v126, v144
	v_fmac_f32_e32 v138, v126, v52
	v_fmac_f32_e32 v136, v127, v145
	v_fmac_f32_e32 v138, v127, v53
	v_fmac_f32_e32 v136, v128, v146
	v_fmac_f32_e32 v138, v128, v54
	v_fmac_f32_e32 v136, v129, v147
	v_fmac_f32_e32 v138, v129, v55
	v_mul_f32_e32 v112, v148, v108
	v_mul_f32_e32 v113, v149, v108
	v_add_f32_dpp v136, v136, v136 quad_perm:[1,0,3,2] row_mask:0xf bank_mask:0xf bound_ctrl:1
	v_add_f32_dpp v139, v137, v137 row_half_mirror row_mask:0xf bank_mask:0xf bound_ctrl:1
	v_add_f32_dpp v139, v138, v138 row_half_mirror row_mask:0xf bank_mask:0xa
	v_add_f32_dpp v136, v136, v136 quad_perm:[2,3,0,1] row_mask:0xf bank_mask:0xf bound_ctrl:1
	v_mul_f32_e32 v114, v150, v108
	v_mul_f32_e32 v115, v151, v108
	v_add_f32_dpp v139, v139, v139 quad_perm:[2,3,0,1] row_mask:0xf bank_mask:0xf bound_ctrl:1
	v_add_f32_dpp v136, v136, v136 row_half_mirror row_mask:0xf bank_mask:0xf bound_ctrl:1
	v_mul_f32_e32 v116, v152, v108
	v_mul_f32_e32 v117, v153, v108
	v_add_f32_dpp v139, v139, v139 quad_perm:[1,0,3,2] row_mask:0xf bank_mask:0xf bound_ctrl:1
	v_mul_f32_e32 v118, v154, v108
	v_mul_f32_e32 v119, v155, v108
	ds_write_b32 v135, v139 offset:3072
	ds_read_b128 v[140:143], v133 offset:15360
	ds_read_b128 v[144:147], v133 offset:15376
	ds_read_b128 v[148:151], v133 offset:31744
	ds_read_b128 v[152:155], v133 offset:31760
	ds_read2st64_b32 v[106:107], v134 offset0:188 offset1:189
	ds_read_b128 v[32:35], v133 offset:6912
	ds_read_b128 v[36:39], v133 offset:6928
	ds_read_b128 v[40:43], v133 offset:23296
	ds_read_b128 v[44:47], v133 offset:23312
	ds_read_b128 v[48:51], v133 offset:39680
	ds_read_b128 v[52:55], v133 offset:39696
	s_waitcnt lgkmcnt(11)
	v_fmac_f32_e32 v112, v184, v136
	v_fmac_f32_e32 v113, v185, v136
	v_fmac_f32_e32 v114, v186, v136
	v_fmac_f32_e32 v115, v187, v136
	v_fmac_f32_e32 v116, v188, v136
	v_fmac_f32_e32 v117, v189, v136
	v_fmac_f32_e32 v118, v190, v136
	v_fmac_f32_e32 v119, v191, v136
	v_fma_f32 v122, v122, v176, v112
	v_fma_f32 v123, v123, v177, v113
	v_fma_f32 v124, v124, v178, v114
	v_fma_f32 v125, v125, v179, v115
	v_fma_f32 v126, v126, v180, v116
	v_fma_f32 v127, v127, v181, v117
	v_fma_f32 v128, v128, v182, v118
	v_fma_f32 v129, v129, v183, v119
	v_mul_f32_e32 v136, v122, v158
	v_mul_f32_e32 v137, v192, v122
	v_fmac_f32_e32 v136, v123, v159
	v_fmac_f32_e32 v137, v123, v193
	v_fmac_f32_e32 v136, v124, v160
	v_fmac_f32_e32 v137, v124, v194
	v_fmac_f32_e32 v136, v125, v161
	v_fmac_f32_e32 v137, v125, v195
	v_fmac_f32_e32 v136, v126, v162
	v_fmac_f32_e32 v137, v126, v196
	v_fmac_f32_e32 v136, v127, v163
	v_fmac_f32_e32 v137, v127, v197
	v_fmac_f32_e32 v136, v128, v164
	v_fmac_f32_e32 v137, v128, v198
	v_fmac_f32_e32 v136, v129, v165
	v_fmac_f32_e32 v137, v129, v199
	v_mul_f32_e32 v112, v166, v109
	v_mul_f32_e32 v113, v167, v109
	v_add_f32_dpp v136, v136, v136 quad_perm:[1,0,3,2] row_mask:0xf bank_mask:0xf bound_ctrl:1
	v_mul_f32_e32 v114, v168, v109
	v_mul_f32_e32 v115, v169, v109
	v_add_f32_dpp v136, v136, v136 quad_perm:[2,3,0,1] row_mask:0xf bank_mask:0xf bound_ctrl:1
	v_mul_f32_e32 v116, v170, v109
	v_mul_f32_e32 v117, v171, v109
	v_add_f32_dpp v136, v136, v136 row_half_mirror row_mask:0xf bank_mask:0xf bound_ctrl:1
	v_mul_f32_e32 v118, v172, v109
	v_mul_f32_e32 v119, v173, v109
	ds_read_b128 v[158:161], v133 offset:15616
	ds_read_b128 v[162:165], v133 offset:15632
	ds_read_b128 v[166:169], v133 offset:32000
	ds_read_b128 v[170:173], v133 offset:32016
	ds_read_b128 v[176:179], v133 offset:7168
	ds_read_b128 v[180:183], v133 offset:7184
	ds_read_b128 v[184:187], v133 offset:23552
	ds_read_b128 v[188:191], v133 offset:23568
	ds_read_b128 v[192:195], v133 offset:39936
	ds_read_b128 v[196:199], v133 offset:39952
	s_waitcnt lgkmcnt(10)
; template <int CTRL> __device__ __forceinline__ float dppf(float x) { return __builtin_bit_cast(float, __builtin_amdgcn_mov_dpp(__builtin_bit_cast(int, x), CTRL, 0xf, 0xf, true)); }
; #define LDOPS(s_) do { const float* p_ = bb + (s_) * 64; w4[(s_) % 3] = *(const f32x4*)(p_); a4[(s_) % 3] = *(const f32x4*)(p_ + 2048); b4[(s_) % 3] = *(const f32x4*)(p_ + 4096); k4[(s_) % 3] = *(const f32x4*)(p_ + 6144); \
;               r4[(s_) % 3] = *(const f32x4*)(p_ + 8192); vv[(s_) % 3] = vb[(s_) * 64]; } while (0)
; __device__ __forceinline__ void scan_block(unsigned char* shm, int sid, int half) {
;     ...
;           for (int s = 0; s < TS; ++s) {
;               const f32x4 a_ = a4[s % 3], w_ = w4[s % 3], b_ = b4[s % 3], k_ = k4[s % 3], r_ = r4[s % 3];
;               const float av[4] = {a_.x, a_.y, a_.z, a_.w}, wv[4] = {w_.x, w_.y, w_.z, w_.w}, bv[4] = {b_.x, b_.y, b_.z, b_.w}, kv[4] = {k_.x, k_.y, k_.z, k_.w}, rv[4] = {r_.x, r_.y, r_.z, r_.w};
;               const float v1 = vv[s % 3];
;               if (s + 2 < TS) LDOPS(s + 2);
;               float t = S[0] * av[0]; t = fmaf(S[1], av[1], t); t = fmaf(S[2], av[2], t); t = fmaf(S[3], av[3], t);
;               t += dppf<0xB1>(t); t += dppf<0x4E>(t); t += dppf<0x141>(t); t += dppf<0x140>(t);
; #pragma unroll
;               for (int q = 0; q < 4; ++q) S[q] = fmaf(S[q], wv[q], fmaf(bv[q], t, kv[q] * v1));
;               float u = S[0] * rv[0]; u = fmaf(S[1], rv[1], u); u = fmaf(S[2], rv[2], u); u = fmaf(S[3], rv[3], u);
;               u += dppf<0xB1>(u); u += dppf<0x4E>(u); u += dppf<0x141>(u); u += dppf<0x140>(u);
;               ys[s * 32] = u;
;           }
	v_fmac_f32_e32 v112, v40, v136
	v_fmac_f32_e32 v113, v41, v136
	v_fmac_f32_e32 v114, v42, v136
	v_fmac_f32_e32 v115, v43, v136
	v_fmac_f32_e32 v116, v44, v136
	v_fmac_f32_e32 v117, v45, v136
	v_fmac_f32_e32 v118, v46, v136
	v_fmac_f32_e32 v119, v47, v136
	v_fma_f32 v122, v122, v32, v112
	v_fma_f32 v123, v123, v33, v113
	v_fma_f32 v124, v124, v34, v114
	v_fma_f32 v125, v125, v35, v115
	v_fma_f32 v126, v126, v36, v116
	v_fma_f32 v127, v127, v37, v117
	v_fma_f32 v128, v128, v38, v118
	v_fma_f32 v129, v129, v39, v119
	v_mul_f32_e32 v136, v122, v140
	v_mul_f32_e32 v138, v48, v122
	v_fmac_f32_e32 v136, v123, v141
	v_fmac_f32_e32 v138, v123, v49
	v_fmac_f32_e32 v136, v124, v142
	v_fmac_f32_e32 v138, v124, v50
	v_fmac_f32_e32 v136, v125, v143
	v_fmac_f32_e32 v138, v125, v51
	v_fmac_f32_e32 v136, v126, v144
	v_fmac_f32_e32 v138, v126, v52
	v_fmac_f32_e32 v136, v127, v145
	v_fmac_f32_e32 v138, v127, v53
	v_fmac_f32_e32 v136, v128, v146
	v_fmac_f32_e32 v138, v128, v54
	v_fmac_f32_e32 v136, v129, v147
	v_fmac_f32_e32 v138, v129, v55
	v_mul_f32_e32 v112, v148, v106
	v_mul_f32_e32 v113, v149, v106
	v_add_f32_dpp v136, v136, v136 quad_perm:[1,0,3,2] row_mask:0xf bank_mask:0xf bound_ctrl:1
	v_add_f32_dpp v139, v137, v137 row_half_mirror row_mask:0xf bank_mask:0xf bound_ctrl:1
	v_add_f32_dpp v139, v138, v138 row_half_mirror row_mask:0xf bank_mask:0xa
	v_add_f32_dpp v136, v136, v136 quad_perm:[2,3,0,1] row_mask:0xf bank_mask:0xf bound_ctrl:1
	v_mul_f32_e32 v114, v150, v106
	v_mul_f32_e32 v115, v151, v106
	v_add_f32_dpp v139, v139, v139 quad_perm:[2,3,0,1] row_mask:0xf bank_mask:0xf bound_ctrl:1
	v_add_f32_dpp v136, v136, v136 row_half_mirror row_mask:0xf bank_mask:0xf bound_ctrl:1
	v_mul_f32_e32 v116, v152, v106
	v_mul_f32_e32 v117, v153, v106
	v_add_f32_dpp v139, v139, v139 quad_perm:[1,0,3,2] row_mask:0xf bank_mask:0xf bound_ctrl:1
	v_mul_f32_e32 v118, v154, v106
	v_mul_f32_e32 v119, v155, v106
	ds_write_b32 v135, v139 offset:3328
	ds_read_b128 v[140:143], v133 offset:15872
	ds_read_b128 v[144:147], v133 offset:15888
	ds_read_b128 v[148:151], v133 offset:32256
	ds_read_b128 v[152:155], v133 offset:32272
	ds_read2st64_b32 v[108:109], v134 offset0:190 offset1:191
	ds_read_b128 v[32:35], v133 offset:7424
	ds_read_b128 v[36:39], v133 offset:7440
	ds_read_b128 v[40:43], v133 offset:23808
	ds_read_b128 v[44:47], v133 offset:23824
	ds_read_b128 v[48:51], v133 offset:40192
	ds_read_b128 v[52:55], v133 offset:40208
	s_waitcnt lgkmcnt(11)
	v_fmac_f32_e32 v112, v184, v136
	v_fmac_f32_e32 v113, v185, v136
	v_fmac_f32_e32 v114, v186, v136
	v_fmac_f32_e32 v115, v187, v136
	v_fmac_f32_e32 v116, v188, v136
	v_fmac_f32_e32 v117, v189, v136
	v_fmac_f32_e32 v118, v190, v136
	v_fmac_f32_e32 v119, v191, v136
	v_fma_f32 v122, v122, v176, v112
	v_fma_f32 v123, v123, v177, v113
	v_fma_f32 v124, v124, v178, v114
	v_fma_f32 v125, v125, v179, v115
	v_fma_f32 v126, v126, v180, v116
	v_fma_f32 v127, v127, v181, v117
	v_fma_f32 v128, v128, v182, v118
	v_fma_f32 v129, v129, v183, v119
	v_mul_f32_e32 v136, v122, v158
	v_mul_f32_e32 v137, v192, v122
	v_fmac_f32_e32 v136, v123, v159
	v_fmac_f32_e32 v137, v123, v193
	v_fmac_f32_e32 v136, v124, v160
	v_fmac_f32_e32 v137, v124, v194
	v_fmac_f32_e32 v136, v125, v161
	v_fmac_f32_e32 v137, v125, v195
	v_fmac_f32_e32 v136, v126, v162
	v_fmac_f32_e32 v137, v126, v196
	v_fmac_f32_e32 v136, v127, v163
	v_fmac_f32_e32 v137, v127, v197
	v_fmac_f32_e32 v136, v128, v164
	v_fmac_f32_e32 v137, v128, v198
	v_fmac_f32_e32 v136, v129, v165
	v_fmac_f32_e32 v137, v129, v199
	v_mul_f32_e32 v112, v166, v107
	v_mul_f32_e32 v113, v167, v107
	v_add_f32_dpp v136, v136, v136 quad_perm:[1,0,3,2] row_mask:0xf bank_mask:0xf bound_ctrl:1
	v_mul_f32_e32 v114, v168, v107
	v_mul_f32_e32 v115, v169, v107
	v_add_f32_dpp v136, v136, v136 quad_perm:[2,3,0,1] row_mask:0xf bank_mask:0xf bound_ctrl:1
	v_mul_f32_e32 v116, v170, v107
	v_mul_f32_e32 v117, v171, v107
	v_add_f32_dpp v136, v136, v136 row_half_mirror row_mask:0xf bank_mask:0xf bound_ctrl:1
	v_mul_f32_e32 v118, v172, v107
	v_mul_f32_e32 v119, v173, v107
	ds_read_b128 v[158:161], v133 offset:16128
	ds_read_b128 v[162:165], v133 offset:16144
	ds_read_b128 v[166:169], v133 offset:32512
	ds_read_b128 v[170:173], v133 offset:32528
	ds_read_b128 v[176:179], v133 offset:7680
	ds_read_b128 v[180:183], v133 offset:7696
	ds_read_b128 v[184:187], v133 offset:24064
	ds_read_b128 v[188:191], v133 offset:24080
	ds_read_b128 v[192:195], v133 offset:40448
	ds_read_b128 v[196:199], v133 offset:40464
	s_waitcnt lgkmcnt(10)
	v_fmac_f32_e32 v112, v40, v136
	v_fmac_f32_e32 v113, v41, v136
	v_fmac_f32_e32 v114, v42, v136
	v_fmac_f32_e32 v115, v43, v136
	v_fmac_f32_e32 v116, v44, v136
	v_fmac_f32_e32 v117, v45, v136
	v_fmac_f32_e32 v118, v46, v136
	v_fmac_f32_e32 v119, v47, v136
	v_fma_f32 v122, v122, v32, v112
	v_fma_f32 v123, v123, v33, v113
	v_fma_f32 v124, v124, v34, v114
	v_fma_f32 v125, v125, v35, v115
	v_fma_f32 v126, v126, v36, v116
	v_fma_f32 v127, v127, v37, v117
	v_fma_f32 v128, v128, v38, v118
	v_fma_f32 v129, v129, v39, v119
	v_mul_f32_e32 v136, v122, v140
	v_mul_f32_e32 v138, v48, v122
	v_fmac_f32_e32 v136, v123, v141
	v_fmac_f32_e32 v138, v123, v49
	v_fmac_f32_e32 v136, v124, v142
	v_fmac_f32_e32 v138, v124, v50
	v_fmac_f32_e32 v136, v125, v143
	v_fmac_f32_e32 v138, v125, v51
	v_fmac_f32_e32 v136, v126, v144
	v_fmac_f32_e32 v138, v126, v52
	v_fmac_f32_e32 v136, v127, v145
	v_fmac_f32_e32 v138, v127, v53
	v_fmac_f32_e32 v136, v128, v146
	v_fmac_f32_e32 v138, v128, v54
	v_fmac_f32_e32 v136, v129, v147
	v_fmac_f32_e32 v138, v129, v55
	v_mul_f32_e32 v112, v148, v108
	v_mul_f32_e32 v113, v149, v108
	v_add_f32_dpp v136, v136, v136 quad_perm:[1,0,3,2] row_mask:0xf bank_mask:0xf bound_ctrl:1
	v_add_f32_dpp v139, v137, v137 row_half_mirror row_mask:0xf bank_mask:0xf bound_ctrl:1
	v_add_f32_dpp v139, v138, v138 row_half_mirror row_mask:0xf bank_mask:0xa
	v_add_f32_dpp v136, v136, v136 quad_perm:[2,3,0,1] row_mask:0xf bank_mask:0xf bound_ctrl:1
	v_mul_f32_e32 v114, v150, v108
	v_mul_f32_e32 v115, v151, v108
	v_add_f32_dpp v139, v139, v139 quad_perm:[2,3,0,1] row_mask:0xf bank_mask:0xf bound_ctrl:1
	v_add_f32_dpp v136, v136, v136 row_half_mirror row_mask:0xf bank_mask:0xf bound_ctrl:1
	v_mul_f32_e32 v116, v152, v108
	v_mul_f32_e32 v117, v153, v108
	v_add_f32_dpp v139, v139, v139 quad_perm:[1,0,3,2] row_mask:0xf bank_mask:0xf bound_ctrl:1
	v_mul_f32_e32 v118, v154, v108
	v_mul_f32_e32 v119, v155, v108
	ds_write_b32 v135, v139 offset:3584
	ds_read_b128 v[32:35], v133 offset:7936
	ds_read_b128 v[36:39], v133 offset:7952
	ds_read_b128 v[40:43], v133 offset:24320
	ds_read_b128 v[44:47], v133 offset:24336
	ds_read_b128 v[48:51], v133 offset:40704
	ds_read_b128 v[52:55], v133 offset:40720
	s_waitcnt lgkmcnt(6)
; template <int CTRL> __device__ __forceinline__ float dppf(float x) { return __builtin_bit_cast(float, __builtin_amdgcn_mov_dpp(__builtin_bit_cast(int, x), CTRL, 0xf, 0xf, true)); }
; #define LDOPS(s_) do { const float* p_ = bb + (s_) * 64; w4[(s_) % 3] = *(const f32x4*)(p_); a4[(s_) % 3] = *(const f32x4*)(p_ + 2048); b4[(s_) % 3] = *(const f32x4*)(p_ + 4096); k4[(s_) % 3] = *(const f32x4*)(p_ + 6144); \
;               r4[(s_) % 3] = *(const f32x4*)(p_ + 8192); vv[(s_) % 3] = vb[(s_) * 64]; } while (0)
; __device__ __forceinline__ void scan_block(unsigned char* shm, int sid, int half) {
;     ...
;           for (int s = 0; s < TS; ++s) {
;               const f32x4 a_ = a4[s % 3], w_ = w4[s % 3], b_ = b4[s % 3], k_ = k4[s % 3], r_ = r4[s % 3];
;               const float av[4] = {a_.x, a_.y, a_.z, a_.w}, wv[4] = {w_.x, w_.y, w_.z, w_.w}, bv[4] = {b_.x, b_.y, b_.z, b_.w}, kv[4] = {k_.x, k_.y, k_.z, k_.w}, rv[4] = {r_.x, r_.y, r_.z, r_.w};
;               const float v1 = vv[s % 3];
;               if (s + 2 < TS) LDOPS(s + 2);
;               float t = S[0] * av[0]; t = fmaf(S[1], av[1], t); t = fmaf(S[2], av[2], t); t = fmaf(S[3], av[3], t);
;               t += dppf<0xB1>(t); t += dppf<0x4E>(t); t += dppf<0x141>(t); t += dppf<0x140>(t);
; #pragma unroll
;               for (int q = 0; q < 4; ++q) S[q] = fmaf(S[q], wv[q], fmaf(bv[q], t, kv[q] * v1));
;               float u = S[0] * rv[0]; u = fmaf(S[1], rv[1], u); u = fmaf(S[2], rv[2], u); u = fmaf(S[3], rv[3], u);
;               u += dppf<0xB1>(u); u += dppf<0x4E>(u); u += dppf<0x141>(u); u += dppf<0x140>(u);
;               ys[s * 32] = u;
	v_fmac_f32_e32 v112, v184, v136
	v_fmac_f32_e32 v113, v185, v136
	v_fmac_f32_e32 v114, v186, v136
	v_fmac_f32_e32 v115, v187, v136
	v_fmac_f32_e32 v116, v188, v136
	v_fmac_f32_e32 v117, v189, v136
	v_fmac_f32_e32 v118, v190, v136
	v_fmac_f32_e32 v119, v191, v136
	v_fma_f32 v122, v122, v176, v112
	v_fma_f32 v123, v123, v177, v113
	v_fma_f32 v124, v124, v178, v114
	v_fma_f32 v125, v125, v179, v115
	v_fma_f32 v126, v126, v180, v116
	v_fma_f32 v127, v127, v181, v117
	v_fma_f32 v128, v128, v182, v118
	v_fma_f32 v129, v129, v183, v119
	v_mul_f32_e32 v136, v122, v158
	v_mul_f32_e32 v137, v192, v122
	v_fmac_f32_e32 v136, v123, v159
	v_fmac_f32_e32 v137, v123, v193
	v_fmac_f32_e32 v136, v124, v160
	v_fmac_f32_e32 v137, v124, v194
	v_fmac_f32_e32 v136, v125, v161
	v_fmac_f32_e32 v137, v125, v195
	v_fmac_f32_e32 v136, v126, v162
	v_fmac_f32_e32 v137, v126, v196
	v_fmac_f32_e32 v136, v127, v163
	v_fmac_f32_e32 v137, v127, v197
	v_fmac_f32_e32 v136, v128, v164
	v_fmac_f32_e32 v137, v128, v198
	v_fmac_f32_e32 v136, v129, v165
	v_fmac_f32_e32 v137, v129, v199
	v_mul_f32_e32 v112, v166, v109
	v_mul_f32_e32 v113, v167, v109
	v_add_f32_dpp v136, v136, v136 quad_perm:[1,0,3,2] row_mask:0xf bank_mask:0xf bound_ctrl:1
	v_mul_f32_e32 v114, v168, v109
	v_mul_f32_e32 v115, v169, v109
	v_add_f32_dpp v136, v136, v136 quad_perm:[2,3,0,1] row_mask:0xf bank_mask:0xf bound_ctrl:1
	v_mul_f32_e32 v116, v170, v109
	v_mul_f32_e32 v117, v171, v109
	v_add_f32_dpp v136, v136, v136 row_half_mirror row_mask:0xf bank_mask:0xf bound_ctrl:1
	v_mul_f32_e32 v118, v172, v109
	v_mul_f32_e32 v119, v173, v109
	s_waitcnt lgkmcnt(0)
	v_fmac_f32_e32 v112, v40, v136
	v_fmac_f32_e32 v113, v41, v136
	v_fmac_f32_e32 v114, v42, v136
	v_fmac_f32_e32 v115, v43, v136
	v_fmac_f32_e32 v116, v44, v136
	v_fmac_f32_e32 v117, v45, v136
	v_fmac_f32_e32 v118, v46, v136
	v_fmac_f32_e32 v119, v47, v136
	v_fma_f32 v122, v122, v32, v112
	v_fma_f32 v123, v123, v33, v113
	v_fma_f32 v124, v124, v34, v114
	v_fma_f32 v125, v125, v35, v115
	v_fma_f32 v126, v126, v36, v116
	v_fma_f32 v127, v127, v37, v117
	v_fma_f32 v128, v128, v38, v118
	v_fma_f32 v129, v129, v39, v119
	v_mul_f32_e32 v138, v48, v122
	v_fmac_f32_e32 v138, v123, v49
	v_fmac_f32_e32 v138, v124, v50
	v_fmac_f32_e32 v138, v125, v51
	v_fmac_f32_e32 v138, v126, v52
	v_fmac_f32_e32 v138, v127, v53
	v_fmac_f32_e32 v138, v128, v54
	v_fmac_f32_e32 v138, v129, v55
	v_add_f32_dpp v139, v137, v137 row_half_mirror row_mask:0xf bank_mask:0xf bound_ctrl:1
	s_nop 0
	v_add_f32_dpp v139, v138, v138 row_half_mirror row_mask:0xf bank_mask:0xa
	s_nop 1
	v_add_f32_dpp v139, v139, v139 quad_perm:[2,3,0,1] row_mask:0xf bank_mask:0xf bound_ctrl:1
	s_nop 1
	v_add_f32_dpp v139, v139, v139 quad_perm:[1,0,3,2] row_mask:0xf bank_mask:0xf bound_ctrl:1
	ds_write_b32 v135, v139 offset:3840
.Lscan_idle:
	s_cbranch_vccnz .LBB0_796
	s_bitcmp1_b32 s10, 0
	s_cselect_b32 s9, 0xc000, 0
	s_waitcnt vmcnt(1)
	v_lshlrev_b32_e32 v12, 16, v80
	v_and_b32_e32 v13, 0xffff0000, v80
	v_lshlrev_b32_e32 v14, 16, v81
	v_and_b32_e32 v15, 0xffff0000, v81
	v_add_u32_e32 v28, s9, v96
	v_lshlrev_b32_e32 v20, 16, v78
	v_and_b32_e32 v21, 0xffff0000, v78
	v_lshlrev_b32_e32 v22, 16, v79
	v_and_b32_e32 v23, 0xffff0000, v79
	v_sub_f32_e32 v15, 1.0, v15
	v_sub_f32_e32 v14, 1.0, v14
	v_sub_f32_e32 v13, 1.0, v13
	v_sub_f32_e32 v12, 1.0, v12
	s_waitcnt vmcnt(0)
	v_lshlrev_b32_e32 v24, 16, v82
	v_and_b32_e32 v25, 0xffff0000, v82
	v_lshlrev_b32_e32 v26, 16, v83
	v_and_b32_e32 v27, 0xffff0000, v83
	ds_write_b128 v28, v[12:15]
	v_xor_b32_e32 v15, 0x80000000, v23
	v_xor_b32_e32 v14, 0x80000000, v22
	v_xor_b32_e32 v13, 0x80000000, v21
	v_xor_b32_e32 v12, 0x80000000, v20
	ds_write_b128 v28, v[12:15] offset:8192
	v_pk_mul_f32 v[14:15], v[26:27], v[22:23]
	v_pk_mul_f32 v[12:13], v[24:25], v[20:21]
	ds_write_b128 v28, v[12:15] offset:16384
	v_pk_add_f32 v[12:13], v[26:27], -1.0 op_sel_hi:[1,0]
	v_pk_add_f32 v[14:15], v[24:25], -1.0 op_sel_hi:[1,0]
	v_lshlrev_b32_e32 v16, 16, v74
	v_and_b32_e32 v17, 0xffff0000, v74
	v_lshlrev_b32_e32 v18, 16, v75
	v_and_b32_e32 v19, 0xffff0000, v75
	v_pk_fma_f32 v[20:21], v[68:69], v[14:15], 1.0 op_sel_hi:[1,1,0]
	v_pk_fma_f32 v[12:13], v[70:71], v[12:13], 1.0 op_sel_hi:[1,1,0]
	v_lshlrev_b32_e32 v4, 16, v72
	v_pk_mul_f32 v[14:15], v[12:13], v[18:19]
	v_pk_mul_f32 v[12:13], v[20:21], v[16:17]
	v_and_b32_e32 v5, 0xffff0000, v72
	v_lshlrev_b32_e32 v6, 16, v73
	v_and_b32_e32 v7, 0xffff0000, v73
	v_lshlrev_b32_e32 v8, 16, v76
	v_and_b32_e32 v9, 0xffff0000, v76
	v_lshlrev_b32_e32 v10, 16, v77
	v_and_b32_e32 v11, 0xffff0000, v77
	ds_write_b128 v28, v[12:15] offset:24576
	ds_write_b128 v28, v[4:7] offset:32768
	ds_write_b128 v28, v[8:11] offset:40960
